# v28 + P2 sample gather loop software-pipelined one chunk ahead: K rows 0-5 and all V rows prefetched into dead VGPRs (v158-v255 pool) and copied at the chunk boundary, K rows 6-15 loaded in place as s
# baseline (speedup 1.0000x reference)
.LBB0_347:
	v_lshlrev_b32_e32 v220, 2, v68
	v_mov_b32_dpp v14, v76 quad_perm:[1,0,3,2] row_mask:0xf bank_mask:0xf bound_ctrl:1
	v_max_f32_e32 v14, v14, v14
	v_max_f32_e32 v15, v76, v76
	v_max_f32_e32 v14, v15, v14
	s_nop 1
	v_mov_b32_dpp v15, v14 quad_perm:[2,3,0,1] row_mask:0xf bank_mask:0xf bound_ctrl:1
	v_max_f32_e32 v15, v15, v15
	v_max_f32_e32 v14, v14, v15
	s_nop 1
	v_mov_b32_dpp v15, v14 row_half_mirror row_mask:0xf bank_mask:0xf bound_ctrl:1
	v_max_f32_e32 v15, v15, v15
	v_max_f32_e32 v14, v14, v15
	s_nop 1
	v_mov_b32_dpp v15, v14 row_mirror row_mask:0xf bank_mask:0xf bound_ctrl:1
	v_max_f32_e32 v15, v15, v15
	v_max_f32_e32 v14, v14, v15
	v_mov_b32_e32 v15, v14
	s_nop 1
	v_permlane16_swap_b32_e32 v14, v15
	v_max_f32_e32 v15, v15, v15
	v_max_f32_e32 v14, v14, v14
	v_max_f32_e32 v14, v14, v15
	v_mov_b32_e32 v15, v14
	s_nop 1
	v_permlane32_swap_b32_e32 v14, v15
	v_max_f32_e32 v15, v15, v15
	v_max_f32_e32 v14, v14, v14
	v_max_f32_e32 v14, v14, v15
	v_cmp_eq_f32_e32 vcc, v76, v14
	s_ff1_i32_b64 s0, vcc
	s_add_i32 s0, s0, 1
	s_cmp_lg_u64 vcc, 0
	s_cselect_b32 s0, s0, 0
	s_add_i32 s0, s0, -1
	s_and_b32 s0, s0, 31
	s_lshl_b32 s1, s0, 1
	s_waitcnt vmcnt(3)
	v_readlane_b32 s6, v71, s1
	s_ashr_i32 s7, s6, 31
	s_lshl_b64 s[6:7], s[6:7], 16
	s_lshl_b64 s[98:99], s[6:7], 2
	s_add_u32 s98, s98, s84
	s_addc_u32 s99, s99, s85
	global_load_dwordx4 v[80:83], v220, s[98:99] nt
	s_lshl_b64 s[98:99], s[6:7], 2
	s_add_u32 s98, s98, s84
	s_addc_u32 s99, s99, s85
	s_add_u32 s98, s98, 0x2000
	s_addc_u32 s99, s99, 0
	global_load_dwordx4 v[84:87], v220, s[98:99] nt
	s_lshl_b64 s[98:99], s[6:7], 2
	s_add_u32 s98, s98, s84
	s_addc_u32 s99, s99, s85
	s_add_u32 s98, s98, 0x4000
	s_addc_u32 s99, s99, 0
	global_load_dwordx4 v[88:91], v220, s[98:99] nt
	s_lshl_b64 s[98:99], s[6:7], 2
	s_add_u32 s98, s98, s84
	s_addc_u32 s99, s99, s85
	s_add_u32 s98, s98, 0x6000
	s_addc_u32 s99, s99, 0
	global_load_dwordx4 v[92:95], v220, s[98:99] nt
	s_lshl_b64 s[98:99], s[6:7], 2
	s_add_u32 s98, s98, s84
	s_addc_u32 s99, s99, s85
	s_add_u32 s98, s98, 0x8000
	s_addc_u32 s99, s99, 0
	global_load_dwordx4 v[96:99], v220, s[98:99] nt
	s_lshl_b64 s[98:99], s[6:7], 2
	s_add_u32 s98, s98, s84
	s_addc_u32 s99, s99, s85
	s_add_u32 s98, s98, 0xa000
	s_addc_u32 s99, s99, 0
	global_load_dwordx4 v[100:103], v220, s[98:99] nt
	s_lshl_b64 s[98:99], s[6:7], 2
	s_add_u32 s98, s98, s84
	s_addc_u32 s99, s99, s85
	s_add_u32 s98, s98, 0xc000
	s_addc_u32 s99, s99, 0
	global_load_dwordx4 v[104:107], v220, s[98:99] nt
	s_lshl_b64 s[98:99], s[6:7], 2
	s_add_u32 s98, s98, s84
	s_addc_u32 s99, s99, s85
	s_add_u32 s98, s98, 0xe000
	s_addc_u32 s99, s99, 0
	global_load_dwordx4 v[108:111], v220, s[98:99] nt
	s_lshl_b64 s[98:99], s[6:7], 2
	s_add_u32 s98, s98, s84
	s_addc_u32 s99, s99, s85
	s_add_u32 s98, s98, 0x10000
	s_addc_u32 s99, s99, 0
	global_load_dwordx4 v[112:115], v220, s[98:99] nt
	s_lshl_b64 s[98:99], s[6:7], 2
	s_add_u32 s98, s98, s84
	s_addc_u32 s99, s99, s85
	s_add_u32 s98, s98, 0x12000
	s_addc_u32 s99, s99, 0
	global_load_dwordx4 v[116:119], v220, s[98:99] nt
	s_lshl_b64 s[98:99], s[6:7], 2
	s_add_u32 s98, s98, s84
	s_addc_u32 s99, s99, s85
	s_add_u32 s98, s98, 0x14000
	s_addc_u32 s99, s99, 0
	global_load_dwordx4 v[120:123], v220, s[98:99] nt
	s_lshl_b64 s[98:99], s[6:7], 2
	s_add_u32 s98, s98, s84
	s_addc_u32 s99, s99, s85
	s_add_u32 s98, s98, 0x16000
	s_addc_u32 s99, s99, 0
	global_load_dwordx4 v[124:127], v220, s[98:99] nt
	s_lshl_b64 s[98:99], s[6:7], 2
	s_add_u32 s98, s98, s84
	s_addc_u32 s99, s99, s85
	s_add_u32 s98, s98, 0x18000
	s_addc_u32 s99, s99, 0
	global_load_dwordx4 v[128:131], v220, s[98:99] nt
	s_lshl_b64 s[98:99], s[6:7], 2
	s_add_u32 s98, s98, s84
	s_addc_u32 s99, s99, s85
	s_add_u32 s98, s98, 0x1a000
	s_addc_u32 s99, s99, 0
	global_load_dwordx4 v[132:135], v220, s[98:99] nt
	s_lshl_b64 s[98:99], s[6:7], 2
	s_add_u32 s98, s98, s84
	s_addc_u32 s99, s99, s85
	s_add_u32 s98, s98, 0x1c000
	s_addc_u32 s99, s99, 0
	global_load_dwordx4 v[136:139], v220, s[98:99] nt
	s_lshl_b64 s[98:99], s[6:7], 2
	s_add_u32 s98, s98, s84
	s_addc_u32 s99, s99, s85
	s_add_u32 s98, s98, 0x1e000
	s_addc_u32 s99, s99, 0
	global_load_dwordx4 v[140:143], v220, s[98:99] nt
	s_lshl_b64 s[98:99], s[6:7], 2
	s_add_u32 s98, s98, s86
	s_addc_u32 s99, s99, s87
	global_load_dwordx4 v[144:147], v220, s[98:99] nt
	s_lshl_b64 s[98:99], s[6:7], 2
	s_add_u32 s98, s98, s86
	s_addc_u32 s99, s99, s87
	s_add_u32 s98, s98, 0x2000
	s_addc_u32 s99, s99, 0
	global_load_dwordx4 v[148:151], v220, s[98:99] nt
	s_lshl_b64 s[98:99], s[6:7], 2
	s_add_u32 s98, s98, s86
	s_addc_u32 s99, s99, s87
	s_add_u32 s98, s98, 0x4000
	s_addc_u32 s99, s99, 0
	global_load_dwordx4 v[152:155], v220, s[98:99] nt
	s_lshl_b64 s[98:99], s[6:7], 2
	s_add_u32 s98, s98, s86
	s_addc_u32 s99, s99, s87
	s_add_u32 s98, s98, 0x6000
	s_addc_u32 s99, s99, 0
	global_load_dwordx4 v[62:65], v220, s[98:99] nt
	s_lshl_b64 s[98:99], s[6:7], 2
	s_add_u32 s98, s98, s86
	s_addc_u32 s99, s99, s87
	s_add_u32 s98, s98, 0x8000
	s_addc_u32 s99, s99, 0
	global_load_dwordx4 v[58:61], v220, s[98:99] nt
	s_lshl_b64 s[98:99], s[6:7], 2
	s_add_u32 s98, s98, s86
	s_addc_u32 s99, s99, s87
	s_add_u32 s98, s98, 0xa000
	s_addc_u32 s99, s99, 0
	global_load_dwordx4 v[54:57], v220, s[98:99] nt
	s_lshl_b64 s[98:99], s[6:7], 2
	s_add_u32 s98, s98, s86
	s_addc_u32 s99, s99, s87
	s_add_u32 s98, s98, 0xc000
	s_addc_u32 s99, s99, 0
	global_load_dwordx4 v[50:53], v220, s[98:99] nt
	s_lshl_b64 s[98:99], s[6:7], 2
	s_add_u32 s98, s98, s86
	s_addc_u32 s99, s99, s87
	s_add_u32 s98, s98, 0xe000
	s_addc_u32 s99, s99, 0
	global_load_dwordx4 v[46:49], v220, s[98:99] nt
	s_lshl_b64 s[98:99], s[6:7], 2
	s_add_u32 s98, s98, s86
	s_addc_u32 s99, s99, s87
	s_add_u32 s98, s98, 0x10000
	s_addc_u32 s99, s99, 0
	global_load_dwordx4 v[42:45], v220, s[98:99] nt
	s_lshl_b64 s[98:99], s[6:7], 2
	s_add_u32 s98, s98, s86
	s_addc_u32 s99, s99, s87
	s_add_u32 s98, s98, 0x12000
	s_addc_u32 s99, s99, 0
	global_load_dwordx4 v[38:41], v220, s[98:99] nt
	s_lshl_b64 s[98:99], s[6:7], 2
	s_add_u32 s98, s98, s86
	s_addc_u32 s99, s99, s87
	s_add_u32 s98, s98, 0x14000
	s_addc_u32 s99, s99, 0
	global_load_dwordx4 v[34:37], v220, s[98:99] nt
	s_lshl_b64 s[98:99], s[6:7], 2
	s_add_u32 s98, s98, s86
	s_addc_u32 s99, s99, s87
	s_add_u32 s98, s98, 0x16000
	s_addc_u32 s99, s99, 0
	global_load_dwordx4 v[30:33], v220, s[98:99] nt
	s_lshl_b64 s[98:99], s[6:7], 2
	s_add_u32 s98, s98, s86
	s_addc_u32 s99, s99, s87
	s_add_u32 s98, s98, 0x18000
	s_addc_u32 s99, s99, 0
	global_load_dwordx4 v[26:29], v220, s[98:99] nt
	s_lshl_b64 s[98:99], s[6:7], 2
	s_add_u32 s98, s98, s86
	s_addc_u32 s99, s99, s87
	s_add_u32 s98, s98, 0x1a000
	s_addc_u32 s99, s99, 0
	global_load_dwordx4 v[22:25], v220, s[98:99] nt
	s_lshl_b64 s[98:99], s[6:7], 2
	s_add_u32 s98, s98, s86
	s_addc_u32 s99, s99, s87
	s_add_u32 s98, s98, 0x1c000
	s_addc_u32 s99, s99, 0
	global_load_dwordx4 v[18:21], v220, s[98:99] nt
	s_lshl_b64 s[98:99], s[6:7], 2
	s_add_u32 s98, s98, s86
	s_addc_u32 s99, s99, s87
	s_add_u32 s98, s98, 0x1e000
	s_addc_u32 s99, s99, 0
	global_load_dwordx4 v[14:17], v220, s[98:99] nt
	s_lshl_b64 s[98:99], s[6:7], 2
	s_add_u32 s98, s98, s84
	s_addc_u32 s99, s99, s85
	s_add_u32 s98, s98, 0x20000
	s_addc_u32 s99, s99, 0
	global_load_dwordx4 v[158:161], v220, s[98:99] nt
	s_lshl_b64 s[98:99], s[6:7], 2
	s_add_u32 s98, s98, s84
	s_addc_u32 s99, s99, s85
	s_add_u32 s98, s98, 0x22000
	s_addc_u32 s99, s99, 0
	global_load_dwordx4 v[162:165], v220, s[98:99] nt
	s_lshl_b64 s[98:99], s[6:7], 2
	s_add_u32 s98, s98, s84
	s_addc_u32 s99, s99, s85
	s_add_u32 s98, s98, 0x24000
	s_addc_u32 s99, s99, 0
	global_load_dwordx4 v[166:169], v220, s[98:99] nt
	s_lshl_b64 s[98:99], s[6:7], 2
	s_add_u32 s98, s98, s84
	s_addc_u32 s99, s99, s85
	s_add_u32 s98, s98, 0x26000
	s_addc_u32 s99, s99, 0
	global_load_dwordx4 v[170:173], v220, s[98:99] nt
	s_lshl_b64 s[98:99], s[6:7], 2
	s_add_u32 s98, s98, s84
	s_addc_u32 s99, s99, s85
	s_add_u32 s98, s98, 0x28000
	s_addc_u32 s99, s99, 0
	global_load_dwordx4 v[174:177], v220, s[98:99] nt
	s_lshl_b64 s[98:99], s[6:7], 2
	s_add_u32 s98, s98, s84
	s_addc_u32 s99, s99, s85
	s_add_u32 s98, s98, 0x2a000
	s_addc_u32 s99, s99, 0
	global_load_dwordx4 v[178:181], v220, s[98:99] nt
	s_lshl_b64 s[98:99], s[6:7], 2
	s_add_u32 s98, s98, s86
	s_addc_u32 s99, s99, s87
	s_add_u32 s98, s98, 0x20000
	s_addc_u32 s99, s99, 0
	global_load_dwordx4 v[182:185], v220, s[98:99] nt
	s_lshl_b64 s[98:99], s[6:7], 2
	s_add_u32 s98, s98, s86
	s_addc_u32 s99, s99, s87
	s_add_u32 s98, s98, 0x22000
	s_addc_u32 s99, s99, 0
	global_load_dwordx4 v[186:189], v220, s[98:99] nt
	s_lshl_b64 s[98:99], s[6:7], 2
	s_add_u32 s98, s98, s86
	s_addc_u32 s99, s99, s87
	s_add_u32 s98, s98, 0x24000
	s_addc_u32 s99, s99, 0
	global_load_dwordx4 v[192:195], v220, s[98:99] nt
	s_lshl_b64 s[98:99], s[6:7], 2
	s_add_u32 s98, s98, s86
	s_addc_u32 s99, s99, s87
	s_add_u32 s98, s98, 0x26000
	s_addc_u32 s99, s99, 0
	global_load_dwordx4 v[196:199], v220, s[98:99] nt
	s_lshl_b64 s[98:99], s[6:7], 2
	s_add_u32 s98, s98, s86
	s_addc_u32 s99, s99, s87
	s_add_u32 s98, s98, 0x28000
	s_addc_u32 s99, s99, 0
	global_load_dwordx4 v[200:203], v220, s[98:99] nt
	s_lshl_b64 s[98:99], s[6:7], 2
	s_add_u32 s98, s98, s86
	s_addc_u32 s99, s99, s87
	s_add_u32 s98, s98, 0x2a000
	s_addc_u32 s99, s99, 0
	global_load_dwordx4 v[204:207], v220, s[98:99] nt
	s_lshl_b64 s[98:99], s[6:7], 2
	s_add_u32 s98, s98, s86
	s_addc_u32 s99, s99, s87
	s_add_u32 s98, s98, 0x2c000
	s_addc_u32 s99, s99, 0
	global_load_dwordx4 v[208:211], v220, s[98:99] nt
	s_lshl_b64 s[98:99], s[6:7], 2
	s_add_u32 s98, s98, s86
	s_addc_u32 s99, s99, s87
	s_add_u32 s98, s98, 0x2e000
	s_addc_u32 s99, s99, 0
	global_load_dwordx4 v[212:215], v220, s[98:99] nt
	s_lshl_b64 s[98:99], s[6:7], 2
	s_add_u32 s98, s98, s86
	s_addc_u32 s99, s99, s87
	s_add_u32 s98, s98, 0x30000
	s_addc_u32 s99, s99, 0
	global_load_dwordx4 v[216:219], v220, s[98:99] nt
	s_lshl_b64 s[98:99], s[6:7], 2
	s_add_u32 s98, s98, s86
	s_addc_u32 s99, s99, s87
	s_add_u32 s98, s98, 0x32000
	s_addc_u32 s99, s99, 0
	global_load_dwordx4 v[224:227], v220, s[98:99] nt
	s_lshl_b64 s[98:99], s[6:7], 2
	s_add_u32 s98, s98, s86
	s_addc_u32 s99, s99, s87
	s_add_u32 s98, s98, 0x34000
	s_addc_u32 s99, s99, 0
	global_load_dwordx4 v[228:231], v220, s[98:99] nt
	s_lshl_b64 s[98:99], s[6:7], 2
	s_add_u32 s98, s98, s86
	s_addc_u32 s99, s99, s87
	s_add_u32 s98, s98, 0x36000
	s_addc_u32 s99, s99, 0
	global_load_dwordx4 v[232:235], v220, s[98:99] nt
	s_lshl_b64 s[98:99], s[6:7], 2
	s_add_u32 s98, s98, s86
	s_addc_u32 s99, s99, s87
	s_add_u32 s98, s98, 0x38000
	s_addc_u32 s99, s99, 0
	global_load_dwordx4 v[236:239], v220, s[98:99] nt
	s_lshl_b64 s[98:99], s[6:7], 2
	s_add_u32 s98, s98, s86
	s_addc_u32 s99, s99, s87
	s_add_u32 s98, s98, 0x3a000
	s_addc_u32 s99, s99, 0
	global_load_dwordx4 v[240:243], v220, s[98:99] nt
	s_lshl_b64 s[98:99], s[6:7], 2
	s_add_u32 s98, s98, s86
	s_addc_u32 s99, s99, s87
	s_add_u32 s98, s98, 0x3c000
	s_addc_u32 s99, s99, 0
	global_load_dwordx4 v[244:247], v220, s[98:99] nt
	s_lshl_b64 s[98:99], s[6:7], 2
	s_add_u32 s98, s98, s86
	s_addc_u32 s99, s99, s87
	s_add_u32 s98, s98, 0x3e000
	s_addc_u32 s99, s99, 0
	global_load_dwordx4 v[252:255], v220, s[98:99] nt
	s_or_b32 s1, s1, 1
	v_readlane_b32 s4, v71, s1
	s_ashr_i32 s5, s4, 31
	s_lshl_b64 s[4:5], s[4:5], 16
	s_add_i32 s13, s13, -1
	s_waitcnt vmcnt(53)
	v_pk_mul_f32 v[82:83], v[8:9], v[82:83]
	v_pk_mul_f32 v[80:81], v[6:7], v[80:81]
	s_nop 0
	v_pk_mov_b32 v[156:157], v[80:81], v[82:83] op_sel:[1,0]
	v_mov_b32_e32 v81, v83
	v_pk_add_f32 v[80:81], v[156:157], v[80:81]
	s_nop 0
	v_add_f32_e32 v79, v80, v81
	s_waitcnt vmcnt(52)
	v_pk_mul_f32 v[80:81], v[8:9], v[86:87]
	v_pk_mul_f32 v[82:83], v[6:7], v[84:85]
	v_add_f32_dpp v79, v79, v79 quad_perm:[1,0,3,2] row_mask:0xf bank_mask:0xf bound_ctrl:1
	v_pk_mov_b32 v[84:85], v[82:83], v[80:81] op_sel:[1,0]
	v_mov_b32_e32 v83, v81
	v_pk_add_f32 v[80:81], v[84:85], v[82:83]
	v_add_f32_dpp v79, v79, v79 quad_perm:[2,3,0,1] row_mask:0xf bank_mask:0xf bound_ctrl:1
	v_add_f32_e32 v80, v80, v81
	s_nop 1
	v_add_f32_dpp v80, v80, v80 quad_perm:[1,0,3,2] row_mask:0xf bank_mask:0xf bound_ctrl:1
	v_add_f32_dpp v79, v79, v79 row_half_mirror row_mask:0xf bank_mask:0xf bound_ctrl:1
	s_nop 0
	v_add_f32_dpp v80, v80, v80 quad_perm:[2,3,0,1] row_mask:0xf bank_mask:0xf bound_ctrl:1
	v_add_f32_dpp v79, v79, v79 row_mirror row_mask:0xf bank_mask:0xf bound_ctrl:1
	v_mul_f32_e32 v156, 0x3e38aa3b, v79
	v_add_f32_dpp v80, v80, v80 row_half_mirror row_mask:0xf bank_mask:0xf bound_ctrl:1
	s_waitcnt vmcnt(51)
	v_pk_mul_f32 v[82:83], v[6:7], v[88:89]
	v_add_f32_dpp v86, v80, v80 row_mirror row_mask:0xf bank_mask:0xf bound_ctrl:1
	v_mul_f32_e32 v80, 0x3e38aa3b, v86
	v_max3_f32 v87, v156, s42, v80
	v_pk_mul_f32 v[80:81], v[8:9], v[90:91]
	s_nop 0
	v_pk_mov_b32 v[84:85], v[82:83], v[80:81] op_sel:[1,0]
	v_mov_b32_e32 v83, v81
	v_pk_add_f32 v[80:81], v[84:85], v[82:83]
	s_nop 0
	v_add_f32_e32 v80, v80, v81
	s_waitcnt vmcnt(50)
	v_pk_mul_f32 v[82:83], v[6:7], v[92:93]
	v_add_f32_dpp v80, v80, v80 quad_perm:[1,0,3,2] row_mask:0xf bank_mask:0xf bound_ctrl:1
	s_nop 1
	v_add_f32_dpp v80, v80, v80 quad_perm:[2,3,0,1] row_mask:0xf bank_mask:0xf bound_ctrl:1
	s_nop 1
	v_add_f32_dpp v80, v80, v80 row_half_mirror row_mask:0xf bank_mask:0xf bound_ctrl:1
	s_nop 1
	v_add_f32_dpp v88, v80, v80 row_mirror row_mask:0xf bank_mask:0xf bound_ctrl:1
	v_pk_mul_f32 v[80:81], v[8:9], v[94:95]
	v_mul_f32_e32 v89, 0x3e38aa3b, v88
	v_pk_mov_b32 v[84:85], v[82:83], v[80:81] op_sel:[1,0]
	v_mov_b32_e32 v83, v81
	v_pk_add_f32 v[80:81], v[84:85], v[82:83]
	s_waitcnt vmcnt(49)
	v_pk_mul_f32 v[82:83], v[6:7], v[96:97]
	v_add_f32_e32 v80, v80, v81
	s_nop 1
	v_add_f32_dpp v80, v80, v80 quad_perm:[1,0,3,2] row_mask:0xf bank_mask:0xf bound_ctrl:1
	s_nop 1
	v_add_f32_dpp v80, v80, v80 quad_perm:[2,3,0,1] row_mask:0xf bank_mask:0xf bound_ctrl:1
	s_nop 1
	v_add_f32_dpp v80, v80, v80 row_half_mirror row_mask:0xf bank_mask:0xf bound_ctrl:1
	s_nop 1
	v_add_f32_dpp v90, v80, v80 row_mirror row_mask:0xf bank_mask:0xf bound_ctrl:1
	v_mul_f32_e32 v80, 0x3e38aa3b, v90
	v_max3_f32 v87, v87, v89, v80
	v_pk_mul_f32 v[80:81], v[8:9], v[98:99]
	s_nop 0
	v_pk_mov_b32 v[84:85], v[82:83], v[80:81] op_sel:[1,0]
	v_mov_b32_e32 v83, v81
	v_pk_add_f32 v[80:81], v[84:85], v[82:83]
	s_waitcnt vmcnt(48)
	v_pk_mul_f32 v[82:83], v[6:7], v[100:101]
	v_add_f32_e32 v80, v80, v81
	s_nop 1
	v_add_f32_dpp v80, v80, v80 quad_perm:[1,0,3,2] row_mask:0xf bank_mask:0xf bound_ctrl:1
	s_nop 1
	v_add_f32_dpp v80, v80, v80 quad_perm:[2,3,0,1] row_mask:0xf bank_mask:0xf bound_ctrl:1
	s_nop 1
	v_add_f32_dpp v80, v80, v80 row_half_mirror row_mask:0xf bank_mask:0xf bound_ctrl:1
	s_nop 1
	v_add_f32_dpp v89, v80, v80 row_mirror row_mask:0xf bank_mask:0xf bound_ctrl:1
	v_pk_mul_f32 v[80:81], v[8:9], v[102:103]
	v_mul_f32_e32 v91, 0x3e38aa3b, v89
	v_pk_mov_b32 v[84:85], v[82:83], v[80:81] op_sel:[1,0]
	v_mov_b32_e32 v83, v81
	v_pk_add_f32 v[80:81], v[84:85], v[82:83]
	s_waitcnt vmcnt(47)
	v_pk_mul_f32 v[82:83], v[6:7], v[104:105]
	s_lshl_b64 s[98:99], s[6:7], 2
	s_add_u32 s98, s98, s84
	s_addc_u32 s99, s99, s85
	s_add_u32 s98, s98, 0x2c000
	s_addc_u32 s99, s99, 0
	global_load_dwordx4 v[102:105], v220, s[98:99] nt
	v_add_f32_e32 v80, v80, v81
	s_nop 1
	v_add_f32_dpp v80, v80, v80 quad_perm:[1,0,3,2] row_mask:0xf bank_mask:0xf bound_ctrl:1
	s_nop 1
	v_add_f32_dpp v80, v80, v80 quad_perm:[2,3,0,1] row_mask:0xf bank_mask:0xf bound_ctrl:1
	s_nop 1
	v_add_f32_dpp v80, v80, v80 row_half_mirror row_mask:0xf bank_mask:0xf bound_ctrl:1
	s_nop 1
	v_add_f32_dpp v92, v80, v80 row_mirror row_mask:0xf bank_mask:0xf bound_ctrl:1
	v_mul_f32_e32 v80, 0x3e38aa3b, v92
	v_max3_f32 v87, v87, v91, v80
	v_pk_mul_f32 v[80:81], v[8:9], v[106:107]
	s_nop 0
	v_pk_mov_b32 v[84:85], v[82:83], v[80:81] op_sel:[1,0]
	v_mov_b32_e32 v83, v81
	v_pk_add_f32 v[80:81], v[84:85], v[82:83]
	s_waitcnt vmcnt(47)
	v_pk_mul_f32 v[82:83], v[6:7], v[108:109]
	s_lshl_b64 s[98:99], s[6:7], 2
	s_add_u32 s98, s98, s84
	s_addc_u32 s99, s99, s85
	s_add_u32 s98, s98, 0x2e000
	s_addc_u32 s99, s99, 0
	global_load_dwordx4 v[106:109], v220, s[98:99] nt
	v_add_f32_e32 v80, v80, v81
	s_nop 1
	v_add_f32_dpp v80, v80, v80 quad_perm:[1,0,3,2] row_mask:0xf bank_mask:0xf bound_ctrl:1
	s_nop 1
	v_add_f32_dpp v80, v80, v80 quad_perm:[2,3,0,1] row_mask:0xf bank_mask:0xf bound_ctrl:1
	s_nop 1
	v_add_f32_dpp v80, v80, v80 row_half_mirror row_mask:0xf bank_mask:0xf bound_ctrl:1
	s_nop 1
	v_add_f32_dpp v91, v80, v80 row_mirror row_mask:0xf bank_mask:0xf bound_ctrl:1
	v_pk_mul_f32 v[80:81], v[8:9], v[110:111]
	v_mul_f32_e32 v93, 0x3e38aa3b, v91
	v_pk_mov_b32 v[84:85], v[82:83], v[80:81] op_sel:[1,0]
	v_mov_b32_e32 v83, v81
	v_pk_add_f32 v[80:81], v[84:85], v[82:83]
	s_waitcnt vmcnt(47)
	v_pk_mul_f32 v[82:83], v[6:7], v[112:113]
	s_lshl_b64 s[98:99], s[6:7], 2
	s_add_u32 s98, s98, s84
	s_addc_u32 s99, s99, s85
	s_add_u32 s98, s98, 0x30000
	s_addc_u32 s99, s99, 0
	global_load_dwordx4 v[110:113], v220, s[98:99] nt
	v_add_f32_e32 v80, v80, v81
	s_nop 1
	v_add_f32_dpp v80, v80, v80 quad_perm:[1,0,3,2] row_mask:0xf bank_mask:0xf bound_ctrl:1
	s_nop 1
	v_add_f32_dpp v80, v80, v80 quad_perm:[2,3,0,1] row_mask:0xf bank_mask:0xf bound_ctrl:1
	s_nop 1
	v_add_f32_dpp v80, v80, v80 row_half_mirror row_mask:0xf bank_mask:0xf bound_ctrl:1
	s_nop 1
	v_add_f32_dpp v94, v80, v80 row_mirror row_mask:0xf bank_mask:0xf bound_ctrl:1
	v_mul_f32_e32 v80, 0x3e38aa3b, v94
	v_max3_f32 v87, v87, v93, v80
	v_pk_mul_f32 v[80:81], v[8:9], v[114:115]
	s_nop 0
	v_pk_mov_b32 v[84:85], v[82:83], v[80:81] op_sel:[1,0]
	v_mov_b32_e32 v83, v81
	v_pk_add_f32 v[80:81], v[84:85], v[82:83]
	s_waitcnt vmcnt(47)
	v_pk_mul_f32 v[82:83], v[6:7], v[116:117]
	s_lshl_b64 s[98:99], s[6:7], 2
	s_add_u32 s98, s98, s84
	s_addc_u32 s99, s99, s85
	s_add_u32 s98, s98, 0x32000
	s_addc_u32 s99, s99, 0
	global_load_dwordx4 v[114:117], v220, s[98:99] nt
	v_add_f32_e32 v80, v80, v81
	s_nop 1
	v_add_f32_dpp v80, v80, v80 quad_perm:[1,0,3,2] row_mask:0xf bank_mask:0xf bound_ctrl:1
	s_nop 1
	v_add_f32_dpp v80, v80, v80 quad_perm:[2,3,0,1] row_mask:0xf bank_mask:0xf bound_ctrl:1
	s_nop 1
	v_add_f32_dpp v80, v80, v80 row_half_mirror row_mask:0xf bank_mask:0xf bound_ctrl:1
	s_nop 1
	v_add_f32_dpp v93, v80, v80 row_mirror row_mask:0xf bank_mask:0xf bound_ctrl:1
	v_pk_mul_f32 v[80:81], v[8:9], v[118:119]
	v_mul_f32_e32 v95, 0x3e38aa3b, v93
	v_pk_mov_b32 v[84:85], v[82:83], v[80:81] op_sel:[1,0]
	v_mov_b32_e32 v83, v81
	v_pk_add_f32 v[80:81], v[84:85], v[82:83]
	s_waitcnt vmcnt(47)
	v_pk_mul_f32 v[82:83], v[6:7], v[120:121]
	s_lshl_b64 s[98:99], s[6:7], 2
	s_add_u32 s98, s98, s84
	s_addc_u32 s99, s99, s85
	s_add_u32 s98, s98, 0x34000
	s_addc_u32 s99, s99, 0
	global_load_dwordx4 v[118:121], v220, s[98:99] nt
	v_add_f32_e32 v80, v80, v81
	s_nop 1
	v_add_f32_dpp v80, v80, v80 quad_perm:[1,0,3,2] row_mask:0xf bank_mask:0xf bound_ctrl:1
	s_nop 1
	v_add_f32_dpp v80, v80, v80 quad_perm:[2,3,0,1] row_mask:0xf bank_mask:0xf bound_ctrl:1
	s_nop 1
	v_add_f32_dpp v80, v80, v80 row_half_mirror row_mask:0xf bank_mask:0xf bound_ctrl:1
	s_nop 1
	v_add_f32_dpp v96, v80, v80 row_mirror row_mask:0xf bank_mask:0xf bound_ctrl:1
	v_mul_f32_e32 v80, 0x3e38aa3b, v96
	v_max3_f32 v87, v87, v95, v80
	v_pk_mul_f32 v[80:81], v[8:9], v[122:123]
	s_nop 0
	v_pk_mov_b32 v[84:85], v[82:83], v[80:81] op_sel:[1,0]
	v_mov_b32_e32 v83, v81
	v_pk_add_f32 v[80:81], v[84:85], v[82:83]
	s_waitcnt vmcnt(47)
	v_pk_mul_f32 v[82:83], v[6:7], v[124:125]
	s_lshl_b64 s[98:99], s[6:7], 2
	s_add_u32 s98, s98, s84
	s_addc_u32 s99, s99, s85
	s_add_u32 s98, s98, 0x36000
	s_addc_u32 s99, s99, 0
	global_load_dwordx4 v[122:125], v220, s[98:99] nt
	v_add_f32_e32 v80, v80, v81
	s_nop 1
	v_add_f32_dpp v80, v80, v80 quad_perm:[1,0,3,2] row_mask:0xf bank_mask:0xf bound_ctrl:1
	s_nop 1
	v_add_f32_dpp v80, v80, v80 quad_perm:[2,3,0,1] row_mask:0xf bank_mask:0xf bound_ctrl:1
	s_nop 1
	v_add_f32_dpp v80, v80, v80 row_half_mirror row_mask:0xf bank_mask:0xf bound_ctrl:1
	s_nop 1
	v_add_f32_dpp v95, v80, v80 row_mirror row_mask:0xf bank_mask:0xf bound_ctrl:1
	v_pk_mul_f32 v[80:81], v[8:9], v[126:127]
	v_mul_f32_e32 v97, 0x3e38aa3b, v95
	v_pk_mov_b32 v[84:85], v[82:83], v[80:81] op_sel:[1,0]
	v_mov_b32_e32 v83, v81
	v_pk_add_f32 v[80:81], v[84:85], v[82:83]
	s_waitcnt vmcnt(47)
	v_pk_mul_f32 v[82:83], v[6:7], v[128:129]
	s_lshl_b64 s[98:99], s[6:7], 2
	s_add_u32 s98, s98, s84
	s_addc_u32 s99, s99, s85
	s_add_u32 s98, s98, 0x38000
	s_addc_u32 s99, s99, 0
	global_load_dwordx4 v[126:129], v220, s[98:99] nt
	v_add_f32_e32 v80, v80, v81
	s_nop 1
	v_add_f32_dpp v80, v80, v80 quad_perm:[1,0,3,2] row_mask:0xf bank_mask:0xf bound_ctrl:1
	s_nop 1
	v_add_f32_dpp v80, v80, v80 quad_perm:[2,3,0,1] row_mask:0xf bank_mask:0xf bound_ctrl:1
	s_nop 1
	v_add_f32_dpp v80, v80, v80 row_half_mirror row_mask:0xf bank_mask:0xf bound_ctrl:1
	s_nop 1
	v_add_f32_dpp v98, v80, v80 row_mirror row_mask:0xf bank_mask:0xf bound_ctrl:1
	v_mul_f32_e32 v80, 0x3e38aa3b, v98
	v_max3_f32 v87, v87, v97, v80
	v_pk_mul_f32 v[80:81], v[8:9], v[130:131]
	s_nop 0
	v_pk_mov_b32 v[84:85], v[82:83], v[80:81] op_sel:[1,0]
	v_mov_b32_e32 v83, v81
	v_pk_add_f32 v[80:81], v[84:85], v[82:83]
	s_waitcnt vmcnt(47)
	v_pk_mul_f32 v[82:83], v[6:7], v[132:133]
	s_lshl_b64 s[98:99], s[6:7], 2
	s_add_u32 s98, s98, s84
	s_addc_u32 s99, s99, s85
	s_add_u32 s98, s98, 0x3a000
	s_addc_u32 s99, s99, 0
	global_load_dwordx4 v[130:133], v220, s[98:99] nt
	v_add_f32_e32 v80, v80, v81
	s_nop 1
	v_add_f32_dpp v80, v80, v80 quad_perm:[1,0,3,2] row_mask:0xf bank_mask:0xf bound_ctrl:1
	s_nop 1
	v_add_f32_dpp v80, v80, v80 quad_perm:[2,3,0,1] row_mask:0xf bank_mask:0xf bound_ctrl:1
	s_nop 1
	v_add_f32_dpp v80, v80, v80 row_half_mirror row_mask:0xf bank_mask:0xf bound_ctrl:1
	s_nop 1
	v_add_f32_dpp v97, v80, v80 row_mirror row_mask:0xf bank_mask:0xf bound_ctrl:1
	v_pk_mul_f32 v[80:81], v[8:9], v[134:135]
	v_mul_f32_e32 v99, 0x3e38aa3b, v97
	v_pk_mov_b32 v[84:85], v[82:83], v[80:81] op_sel:[1,0]
	v_mov_b32_e32 v83, v81
	v_pk_add_f32 v[80:81], v[84:85], v[82:83]
	s_waitcnt vmcnt(47)
	v_pk_mul_f32 v[82:83], v[6:7], v[136:137]
	s_lshl_b64 s[98:99], s[6:7], 2
	s_add_u32 s98, s98, s84
	s_addc_u32 s99, s99, s85
	s_add_u32 s98, s98, 0x3c000
	s_addc_u32 s99, s99, 0
	global_load_dwordx4 v[134:137], v220, s[98:99] nt
	v_add_f32_e32 v80, v80, v81
	s_nop 1
	v_add_f32_dpp v80, v80, v80 quad_perm:[1,0,3,2] row_mask:0xf bank_mask:0xf bound_ctrl:1
	s_nop 1
	v_add_f32_dpp v80, v80, v80 quad_perm:[2,3,0,1] row_mask:0xf bank_mask:0xf bound_ctrl:1
	s_nop 1
	v_add_f32_dpp v80, v80, v80 row_half_mirror row_mask:0xf bank_mask:0xf bound_ctrl:1
	s_nop 1
	v_add_f32_dpp v100, v80, v80 row_mirror row_mask:0xf bank_mask:0xf bound_ctrl:1
	v_mul_f32_e32 v80, 0x3e38aa3b, v100
	v_max3_f32 v87, v87, v99, v80
	v_pk_mul_f32 v[80:81], v[8:9], v[138:139]
	s_nop 0
	v_pk_mov_b32 v[84:85], v[82:83], v[80:81] op_sel:[1,0]
	v_mov_b32_e32 v83, v81
	v_pk_add_f32 v[80:81], v[84:85], v[82:83]
	s_waitcnt vmcnt(47)
	v_pk_mul_f32 v[82:83], v[6:7], v[140:141]
	s_lshl_b64 s[98:99], s[6:7], 2
	s_add_u32 s98, s98, s84
	s_addc_u32 s99, s99, s85
	s_add_u32 s98, s98, 0x3e000
	s_addc_u32 s99, s99, 0
	global_load_dwordx4 v[138:141], v220, s[98:99] nt
	v_add_f32_e32 v80, v80, v81
	s_nop 1
	v_add_f32_dpp v80, v80, v80 quad_perm:[1,0,3,2] row_mask:0xf bank_mask:0xf bound_ctrl:1
	s_nop 1
	v_add_f32_dpp v80, v80, v80 quad_perm:[2,3,0,1] row_mask:0xf bank_mask:0xf bound_ctrl:1
	s_nop 1
	v_add_f32_dpp v80, v80, v80 row_half_mirror row_mask:0xf bank_mask:0xf bound_ctrl:1
	s_nop 1
	v_add_f32_dpp v99, v80, v80 row_mirror row_mask:0xf bank_mask:0xf bound_ctrl:1
	v_pk_mul_f32 v[80:81], v[8:9], v[142:143]
	v_mul_f32_e32 v101, 0x3e38aa3b, v99
	v_pk_mov_b32 v[84:85], v[82:83], v[80:81] op_sel:[1,0]
	v_mov_b32_e32 v83, v81
	v_pk_add_f32 v[80:81], v[84:85], v[82:83]
	s_nop 0
	v_add_f32_e32 v80, v80, v81
	s_nop 1
	v_add_f32_dpp v80, v80, v80 quad_perm:[1,0,3,2] row_mask:0xf bank_mask:0xf bound_ctrl:1
	s_nop 1
	v_add_f32_dpp v80, v80, v80 quad_perm:[2,3,0,1] row_mask:0xf bank_mask:0xf bound_ctrl:1
	s_nop 1
	v_add_f32_dpp v80, v80, v80 row_half_mirror row_mask:0xf bank_mask:0xf bound_ctrl:1
	s_nop 1
	v_add_f32_dpp v84, v80, v80 row_mirror row_mask:0xf bank_mask:0xf bound_ctrl:1
	v_mul_f32_e32 v80, 0x3e38aa3b, v84
	v_max3_f32 v80, v87, v101, v80
	v_mov_b32_e32 v81, v80
	s_nop 1
	v_permlane16_swap_b32_e32 v80, v81
	v_max_f32_e32 v81, v81, v81
	v_max_f32_e32 v80, v80, v80
	v_max_f32_e32 v80, v80, v81
	v_mov_b32_e32 v81, v80
	s_nop 1
	v_permlane32_swap_b32_e32 v80, v81
	v_max3_f32 v156, v78, v80, v81
	v_fma_f32 v79, v79, s41, -v156
	v_sub_f32_e32 v78, v78, v156
	v_exp_f32_e32 v80, v79
	v_exp_f32_e32 v78, v78
	v_mov_b32_e32 v79, v80
	v_fmac_f32_e32 v79, v69, v78
	s_waitcnt vmcnt(47)
	v_pk_mul_f32 v[82:83], v[146:147], v[80:81] op_sel_hi:[1,0]
	v_pk_mul_f32 v[80:81], v[144:145], v[80:81] op_sel_hi:[1,0]
	v_fma_f32 v69, v86, s41, -v156
	v_pk_fma_f32 v[72:73], v[72:73], v[78:79], v[80:81] op_sel_hi:[1,0,1]
	v_pk_fma_f32 v[74:75], v[74:75], v[78:79], v[82:83] op_sel_hi:[1,0,1]
	v_exp_f32_e32 v78, v69
	s_nop 0
	v_add_f32_e32 v69, v78, v79
	s_waitcnt vmcnt(46)
	v_pk_fma_f32 v[74:75], v[150:151], v[78:79], v[74:75] op_sel_hi:[1,0,1]
	v_pk_fma_f32 v[72:73], v[148:149], v[78:79], v[72:73] op_sel_hi:[1,0,1]
	v_fma_f32 v78, v88, s41, -v156
	v_exp_f32_e32 v78, v78
	s_nop 0
	v_add_f32_e32 v69, v78, v69
	s_waitcnt vmcnt(45)
	v_pk_fma_f32 v[72:73], v[152:153], v[78:79], v[72:73] op_sel_hi:[1,0,1]
	v_pk_fma_f32 v[74:75], v[154:155], v[78:79], v[74:75] op_sel_hi:[1,0,1]
	v_fma_f32 v78, v90, s41, -v156
	v_exp_f32_e32 v78, v78
	s_waitcnt vmcnt(44)
	v_pk_fma_f32 v[62:63], v[62:63], v[78:79], v[72:73] op_sel_hi:[1,0,1]
	v_fma_f32 v72, v89, s41, -v156
	v_exp_f32_e32 v72, v72
	v_add_f32_e32 v69, v78, v69
	v_pk_fma_f32 v[64:65], v[64:65], v[78:79], v[74:75] op_sel_hi:[1,0,1]
	s_waitcnt vmcnt(43)
	v_pk_fma_f32 v[58:59], v[58:59], v[72:73], v[62:63] op_sel_hi:[1,0,1]
	v_fma_f32 v62, v92, s41, -v156
	v_exp_f32_e32 v62, v62
	v_add_f32_e32 v69, v72, v69
	v_pk_fma_f32 v[60:61], v[60:61], v[72:73], v[64:65] op_sel_hi:[1,0,1]
	v_add_f32_e32 v63, v62, v69
	s_waitcnt vmcnt(42)
	v_pk_fma_f32 v[54:55], v[54:55], v[62:63], v[58:59] op_sel_hi:[1,0,1]
	v_fma_f32 v58, v91, s41, -v156
	v_exp_f32_e32 v58, v58
	v_pk_fma_f32 v[56:57], v[56:57], v[62:63], v[60:61] op_sel_hi:[1,0,1]
	v_add_f32_e32 v59, v58, v63
	s_waitcnt vmcnt(41)
	v_pk_fma_f32 v[50:51], v[50:51], v[58:59], v[54:55] op_sel_hi:[1,0,1]
	v_fma_f32 v54, v94, s41, -v156
	v_exp_f32_e32 v54, v54
	v_pk_fma_f32 v[52:53], v[52:53], v[58:59], v[56:57] op_sel_hi:[1,0,1]
	v_add_f32_e32 v55, v54, v59
	s_waitcnt vmcnt(40)
	v_pk_fma_f32 v[46:47], v[46:47], v[54:55], v[50:51] op_sel_hi:[1,0,1]
	v_fma_f32 v50, v93, s41, -v156
	v_exp_f32_e32 v50, v50
	v_pk_fma_f32 v[48:49], v[48:49], v[54:55], v[52:53] op_sel_hi:[1,0,1]
	v_add_f32_e32 v51, v50, v55
	s_waitcnt vmcnt(39)
	v_pk_fma_f32 v[42:43], v[42:43], v[50:51], v[46:47] op_sel_hi:[1,0,1]
	v_fma_f32 v46, v96, s41, -v156
	v_exp_f32_e32 v46, v46
	v_pk_fma_f32 v[44:45], v[44:45], v[50:51], v[48:49] op_sel_hi:[1,0,1]
	v_add_f32_e32 v47, v46, v51
	s_waitcnt vmcnt(38)
	v_pk_fma_f32 v[38:39], v[38:39], v[46:47], v[42:43] op_sel_hi:[1,0,1]
	v_fma_f32 v42, v95, s41, -v156
	v_exp_f32_e32 v42, v42
	v_pk_fma_f32 v[40:41], v[40:41], v[46:47], v[44:45] op_sel_hi:[1,0,1]
	v_add_f32_e32 v43, v42, v47
	s_waitcnt vmcnt(37)
	v_pk_fma_f32 v[34:35], v[34:35], v[42:43], v[38:39] op_sel_hi:[1,0,1]
	v_fma_f32 v38, v98, s41, -v156
	v_exp_f32_e32 v38, v38
	v_pk_fma_f32 v[36:37], v[36:37], v[42:43], v[40:41] op_sel_hi:[1,0,1]
	v_add_f32_e32 v39, v38, v43
	s_waitcnt vmcnt(36)
	v_pk_fma_f32 v[30:31], v[30:31], v[38:39], v[34:35] op_sel_hi:[1,0,1]
	v_fma_f32 v34, v97, s41, -v156
	v_exp_f32_e32 v34, v34
	v_pk_fma_f32 v[32:33], v[32:33], v[38:39], v[36:37] op_sel_hi:[1,0,1]
	v_add_f32_e32 v35, v34, v39
	s_waitcnt vmcnt(35)
	v_pk_fma_f32 v[26:27], v[26:27], v[34:35], v[30:31] op_sel_hi:[1,0,1]
	v_fma_f32 v30, v100, s41, -v156
	v_exp_f32_e32 v30, v30
	v_pk_fma_f32 v[28:29], v[28:29], v[34:35], v[32:33] op_sel_hi:[1,0,1]
	v_add_f32_e32 v31, v30, v35
	s_waitcnt vmcnt(34)
	v_pk_fma_f32 v[22:23], v[22:23], v[30:31], v[26:27] op_sel_hi:[1,0,1]
	v_fma_f32 v26, v99, s41, -v156
	v_exp_f32_e32 v26, v26
	v_pk_fma_f32 v[24:25], v[24:25], v[30:31], v[28:29] op_sel_hi:[1,0,1]
	v_add_f32_e32 v27, v26, v31
	s_waitcnt vmcnt(33)
	v_pk_fma_f32 v[18:19], v[18:19], v[26:27], v[22:23] op_sel_hi:[1,0,1]
	v_fma_f32 v22, v84, s41, -v156
	s_waitcnt vmcnt(31)
	v_mov_b64_e32 v[78:79], v[158:159]
	v_mov_b64_e32 v[80:81], v[160:161]
	s_waitcnt vmcnt(30)
	v_mov_b64_e32 v[82:83], v[162:163]
	v_mov_b64_e32 v[84:85], v[164:165]
	s_waitcnt vmcnt(29)
	v_mov_b64_e32 v[86:87], v[166:167]
	v_mov_b64_e32 v[88:89], v[168:169]
	s_waitcnt vmcnt(28)
	v_mov_b64_e32 v[90:91], v[170:171]
	v_mov_b64_e32 v[92:93], v[172:173]
	s_waitcnt vmcnt(27)
	v_mov_b64_e32 v[94:95], v[174:175]
	v_mov_b64_e32 v[96:97], v[176:177]
	s_waitcnt vmcnt(26)
	v_mov_b64_e32 v[98:99], v[178:179]
	v_mov_b64_e32 v[100:101], v[180:181]
	s_waitcnt vmcnt(25)
	v_mov_b64_e32 v[142:143], v[182:183]
	v_mov_b64_e32 v[144:145], v[184:185]
	s_waitcnt vmcnt(24)
	v_mov_b64_e32 v[146:147], v[186:187]
	v_mov_b64_e32 v[148:149], v[188:189]
	s_waitcnt vmcnt(23)
	v_mov_b64_e32 v[150:151], v[192:193]
	v_mov_b64_e32 v[152:153], v[194:195]
	s_waitcnt vmcnt(22)
	v_mov_b64_e32 v[62:63], v[196:197]
	v_mov_b64_e32 v[64:65], v[198:199]
	s_waitcnt vmcnt(21)
	v_mov_b64_e32 v[58:59], v[200:201]
	v_mov_b64_e32 v[60:61], v[202:203]
	s_waitcnt vmcnt(20)
	v_mov_b64_e32 v[54:55], v[204:205]
	v_mov_b64_e32 v[56:57], v[206:207]
	s_waitcnt vmcnt(19)
	v_mov_b64_e32 v[50:51], v[208:209]
	v_mov_b64_e32 v[52:53], v[210:211]
	s_waitcnt vmcnt(18)
	v_mov_b64_e32 v[46:47], v[212:213]
	v_mov_b64_e32 v[48:49], v[214:215]
	s_waitcnt vmcnt(17)
	v_mov_b64_e32 v[42:43], v[216:217]
	v_mov_b64_e32 v[44:45], v[218:219]
	s_waitcnt vmcnt(16)
	v_mov_b64_e32 v[38:39], v[224:225]
	v_mov_b64_e32 v[40:41], v[226:227]
	s_waitcnt vmcnt(15)
	v_mov_b64_e32 v[34:35], v[228:229]
	v_mov_b64_e32 v[36:37], v[230:231]
	s_waitcnt vmcnt(14)
	v_mov_b64_e32 v[30:31], v[232:233]
	v_mov_b64_e32 v[32:33], v[234:235]
	v_exp_f32_e32 v22, v22
	v_pk_fma_f32 v[20:21], v[20:21], v[26:27], v[24:25] op_sel_hi:[1,0,1]
	v_pk_fma_f32 v[74:75], v[14:15], v[22:23], v[18:19] op_sel_hi:[1,0,1]
	v_pk_fma_f32 v[72:73], v[16:17], v[22:23], v[20:21] op_sel_hi:[1,0,1]
	s_waitcnt vmcnt(11)
	v_mov_b64_e32 v[18:19], v[244:245]
	v_mov_b64_e32 v[20:21], v[246:247]
	s_waitcnt vmcnt(10)
	v_mov_b64_e32 v[14:15], v[252:253]
	v_mov_b64_e32 v[16:17], v[254:255]
	v_add_f32_e32 v69, v22, v27
	v_mov_b64_e32 v[26:27], v[236:237]
	v_mov_b64_e32 v[28:29], v[238:239]
	v_mov_b64_e32 v[22:23], v[240:241]
	v_mov_b64_e32 v[24:25], v[242:243]
	s_lshl_b64 s[98:99], s[4:5], 2
	s_add_u32 s98, s98, s84
	s_addc_u32 s99, s99, s85
	global_load_dwordx4 v[158:161], v220, s[98:99] nt
	s_lshl_b64 s[98:99], s[4:5], 2
	s_add_u32 s98, s98, s84
	s_addc_u32 s99, s99, s85
	s_add_u32 s98, s98, 0x2000
	s_addc_u32 s99, s99, 0
	global_load_dwordx4 v[162:165], v220, s[98:99] nt
	s_lshl_b64 s[98:99], s[4:5], 2
	s_add_u32 s98, s98, s84
	s_addc_u32 s99, s99, s85
	s_add_u32 s98, s98, 0x4000
	s_addc_u32 s99, s99, 0
	global_load_dwordx4 v[166:169], v220, s[98:99] nt
	s_lshl_b64 s[98:99], s[4:5], 2
	s_add_u32 s98, s98, s84
	s_addc_u32 s99, s99, s85
	s_add_u32 s98, s98, 0x6000
	s_addc_u32 s99, s99, 0
	global_load_dwordx4 v[170:173], v220, s[98:99] nt
	s_lshl_b64 s[98:99], s[4:5], 2
	s_add_u32 s98, s98, s84
	s_addc_u32 s99, s99, s85
	s_add_u32 s98, s98, 0x8000
	s_addc_u32 s99, s99, 0
	global_load_dwordx4 v[174:177], v220, s[98:99] nt
	s_lshl_b64 s[98:99], s[4:5], 2
	s_add_u32 s98, s98, s84
	s_addc_u32 s99, s99, s85
	s_add_u32 s98, s98, 0xa000
	s_addc_u32 s99, s99, 0
	global_load_dwordx4 v[178:181], v220, s[98:99] nt
	s_lshl_b64 s[98:99], s[4:5], 2
	s_add_u32 s98, s98, s86
	s_addc_u32 s99, s99, s87
	global_load_dwordx4 v[182:185], v220, s[98:99] nt
	s_lshl_b64 s[98:99], s[4:5], 2
	s_add_u32 s98, s98, s86
	s_addc_u32 s99, s99, s87
	s_add_u32 s98, s98, 0x2000
	s_addc_u32 s99, s99, 0
	global_load_dwordx4 v[186:189], v220, s[98:99] nt
	s_lshl_b64 s[98:99], s[4:5], 2
	s_add_u32 s98, s98, s86
	s_addc_u32 s99, s99, s87
	s_add_u32 s98, s98, 0x4000
	s_addc_u32 s99, s99, 0
	global_load_dwordx4 v[192:195], v220, s[98:99] nt
	s_lshl_b64 s[98:99], s[4:5], 2
	s_add_u32 s98, s98, s86
	s_addc_u32 s99, s99, s87
	s_add_u32 s98, s98, 0x6000
	s_addc_u32 s99, s99, 0
	global_load_dwordx4 v[196:199], v220, s[98:99] nt
	s_lshl_b64 s[98:99], s[4:5], 2
	s_add_u32 s98, s98, s86
	s_addc_u32 s99, s99, s87
	s_add_u32 s98, s98, 0x8000
	s_addc_u32 s99, s99, 0
	global_load_dwordx4 v[200:203], v220, s[98:99] nt
	s_lshl_b64 s[98:99], s[4:5], 2
	s_add_u32 s98, s98, s86
	s_addc_u32 s99, s99, s87
	s_add_u32 s98, s98, 0xa000
	s_addc_u32 s99, s99, 0
	global_load_dwordx4 v[204:207], v220, s[98:99] nt
	s_lshl_b64 s[98:99], s[4:5], 2
	s_add_u32 s98, s98, s86
	s_addc_u32 s99, s99, s87
	s_add_u32 s98, s98, 0xc000
	s_addc_u32 s99, s99, 0
	global_load_dwordx4 v[208:211], v220, s[98:99] nt
	s_lshl_b64 s[98:99], s[4:5], 2
	s_add_u32 s98, s98, s86
	s_addc_u32 s99, s99, s87
	s_add_u32 s98, s98, 0xe000
	s_addc_u32 s99, s99, 0
	global_load_dwordx4 v[212:215], v220, s[98:99] nt
	s_lshl_b64 s[98:99], s[4:5], 2
	s_add_u32 s98, s98, s86
	s_addc_u32 s99, s99, s87
	s_add_u32 s98, s98, 0x10000
	s_addc_u32 s99, s99, 0
	global_load_dwordx4 v[216:219], v220, s[98:99] nt
	s_lshl_b64 s[98:99], s[4:5], 2
	s_add_u32 s98, s98, s86
	s_addc_u32 s99, s99, s87
	s_add_u32 s98, s98, 0x12000
	s_addc_u32 s99, s99, 0
	global_load_dwordx4 v[224:227], v220, s[98:99] nt
	s_lshl_b64 s[98:99], s[4:5], 2
	s_add_u32 s98, s98, s86
	s_addc_u32 s99, s99, s87
	s_add_u32 s98, s98, 0x14000
	s_addc_u32 s99, s99, 0
	global_load_dwordx4 v[228:231], v220, s[98:99] nt
	s_lshl_b64 s[98:99], s[4:5], 2
	s_add_u32 s98, s98, s86
	s_addc_u32 s99, s99, s87
	s_add_u32 s98, s98, 0x16000
	s_addc_u32 s99, s99, 0
	global_load_dwordx4 v[232:235], v220, s[98:99] nt
	s_lshl_b64 s[98:99], s[4:5], 2
	s_add_u32 s98, s98, s86
	s_addc_u32 s99, s99, s87
	s_add_u32 s98, s98, 0x18000
	s_addc_u32 s99, s99, 0
	global_load_dwordx4 v[236:239], v220, s[98:99] nt
	s_lshl_b64 s[98:99], s[4:5], 2
	s_add_u32 s98, s98, s86
	s_addc_u32 s99, s99, s87
	s_add_u32 s98, s98, 0x1a000
	s_addc_u32 s99, s99, 0
	global_load_dwordx4 v[240:243], v220, s[98:99] nt
	s_lshl_b64 s[98:99], s[4:5], 2
	s_add_u32 s98, s98, s86
	s_addc_u32 s99, s99, s87
	s_add_u32 s98, s98, 0x1c000
	s_addc_u32 s99, s99, 0
	global_load_dwordx4 v[244:247], v220, s[98:99] nt
	s_lshl_b64 s[98:99], s[4:5], 2
	s_add_u32 s98, s98, s86
	s_addc_u32 s99, s99, s87
	s_add_u32 s98, s98, 0x1e000
	s_addc_u32 s99, s99, 0
	global_load_dwordx4 v[252:255], v220, s[98:99] nt
	v_pk_mul_f32 v[80:81], v[8:9], v[80:81]
	v_pk_mul_f32 v[78:79], v[6:7], v[78:79]
	s_nop 0
	v_pk_mov_b32 v[154:155], v[78:79], v[80:81] op_sel:[1,0]
	v_mov_b32_e32 v79, v81
	v_pk_add_f32 v[78:79], v[154:155], v[78:79]
	s_nop 0
	v_add_f32_e32 v78, v78, v79
	s_nop 1
	v_add_f32_dpp v78, v78, v78 quad_perm:[1,0,3,2] row_mask:0xf bank_mask:0xf bound_ctrl:1
	s_nop 1
	v_add_f32_dpp v78, v78, v78 quad_perm:[2,3,0,1] row_mask:0xf bank_mask:0xf bound_ctrl:1
	s_nop 1
	v_add_f32_dpp v78, v78, v78 row_half_mirror row_mask:0xf bank_mask:0xf bound_ctrl:1
	v_pk_mul_f32 v[80:81], v[6:7], v[82:83]
	s_nop 0
	v_add_f32_dpp v154, v78, v78 row_mirror row_mask:0xf bank_mask:0xf bound_ctrl:1
	v_pk_mul_f32 v[78:79], v[8:9], v[84:85]
	s_nop 0
	v_pk_mov_b32 v[82:83], v[80:81], v[78:79] op_sel:[1,0]
	v_mov_b32_e32 v81, v79
	v_pk_add_f32 v[78:79], v[82:83], v[80:81]
	s_nop 0
	v_add_f32_e32 v78, v78, v79
	v_mul_f32_e32 v155, 0x3e38aa3b, v154
	s_nop 0
	v_add_f32_dpp v78, v78, v78 quad_perm:[1,0,3,2] row_mask:0xf bank_mask:0xf bound_ctrl:1
	v_pk_mul_f32 v[80:81], v[6:7], v[86:87]
	s_nop 0
	v_add_f32_dpp v78, v78, v78 quad_perm:[2,3,0,1] row_mask:0xf bank_mask:0xf bound_ctrl:1
	s_nop 1
	v_add_f32_dpp v78, v78, v78 row_half_mirror row_mask:0xf bank_mask:0xf bound_ctrl:1
	s_nop 1
	v_add_f32_dpp v84, v78, v78 row_mirror row_mask:0xf bank_mask:0xf bound_ctrl:1
	v_mul_f32_e32 v78, 0x3e38aa3b, v84
	v_max3_f32 v85, v155, s42, v78
	v_pk_mul_f32 v[78:79], v[8:9], v[88:89]
	s_nop 0
	v_pk_mov_b32 v[82:83], v[80:81], v[78:79] op_sel:[1,0]
	v_mov_b32_e32 v81, v79
	v_pk_add_f32 v[78:79], v[82:83], v[80:81]
	v_pk_mul_f32 v[80:81], v[6:7], v[90:91]
	v_add_f32_e32 v78, v78, v79
	s_nop 1
	v_add_f32_dpp v78, v78, v78 quad_perm:[1,0,3,2] row_mask:0xf bank_mask:0xf bound_ctrl:1
	s_nop 1
	v_add_f32_dpp v78, v78, v78 quad_perm:[2,3,0,1] row_mask:0xf bank_mask:0xf bound_ctrl:1
	s_nop 1
	v_add_f32_dpp v78, v78, v78 row_half_mirror row_mask:0xf bank_mask:0xf bound_ctrl:1
	s_nop 1
	v_add_f32_dpp v86, v78, v78 row_mirror row_mask:0xf bank_mask:0xf bound_ctrl:1
	v_pk_mul_f32 v[78:79], v[8:9], v[92:93]
	v_mul_f32_e32 v87, 0x3e38aa3b, v86
	v_pk_mov_b32 v[82:83], v[80:81], v[78:79] op_sel:[1,0]
	v_mov_b32_e32 v81, v79
	v_pk_add_f32 v[78:79], v[82:83], v[80:81]
	v_pk_mul_f32 v[80:81], v[6:7], v[94:95]
	v_add_f32_e32 v78, v78, v79
	s_nop 1
	v_add_f32_dpp v78, v78, v78 quad_perm:[1,0,3,2] row_mask:0xf bank_mask:0xf bound_ctrl:1
	s_nop 1
	v_add_f32_dpp v78, v78, v78 quad_perm:[2,3,0,1] row_mask:0xf bank_mask:0xf bound_ctrl:1
	s_nop 1
	v_add_f32_dpp v78, v78, v78 row_half_mirror row_mask:0xf bank_mask:0xf bound_ctrl:1
	s_nop 1
	v_add_f32_dpp v88, v78, v78 row_mirror row_mask:0xf bank_mask:0xf bound_ctrl:1
	v_mul_f32_e32 v78, 0x3e38aa3b, v88
	v_max3_f32 v85, v85, v87, v78
	v_pk_mul_f32 v[78:79], v[8:9], v[96:97]
	s_nop 0
	v_pk_mov_b32 v[82:83], v[80:81], v[78:79] op_sel:[1,0]
	v_mov_b32_e32 v81, v79
	v_pk_add_f32 v[78:79], v[82:83], v[80:81]
	v_pk_mul_f32 v[80:81], v[6:7], v[98:99]
	v_add_f32_e32 v78, v78, v79
	s_nop 1
	v_add_f32_dpp v78, v78, v78 quad_perm:[1,0,3,2] row_mask:0xf bank_mask:0xf bound_ctrl:1
	s_nop 1
	v_add_f32_dpp v78, v78, v78 quad_perm:[2,3,0,1] row_mask:0xf bank_mask:0xf bound_ctrl:1
	s_nop 1
	v_add_f32_dpp v78, v78, v78 row_half_mirror row_mask:0xf bank_mask:0xf bound_ctrl:1
	s_nop 1
	v_add_f32_dpp v87, v78, v78 row_mirror row_mask:0xf bank_mask:0xf bound_ctrl:1
	v_pk_mul_f32 v[78:79], v[8:9], v[100:101]
	v_mul_f32_e32 v89, 0x3e38aa3b, v87
	v_pk_mov_b32 v[82:83], v[80:81], v[78:79] op_sel:[1,0]
	v_mov_b32_e32 v81, v79
	v_pk_add_f32 v[78:79], v[82:83], v[80:81]
	s_waitcnt vmcnt(31)
	v_pk_mul_f32 v[80:81], v[6:7], v[102:103]
	v_add_f32_e32 v78, v78, v79
	s_nop 1
	v_add_f32_dpp v78, v78, v78 quad_perm:[1,0,3,2] row_mask:0xf bank_mask:0xf bound_ctrl:1
	s_nop 1
	v_add_f32_dpp v78, v78, v78 quad_perm:[2,3,0,1] row_mask:0xf bank_mask:0xf bound_ctrl:1
	s_nop 1
	v_add_f32_dpp v78, v78, v78 row_half_mirror row_mask:0xf bank_mask:0xf bound_ctrl:1
	s_nop 1
	v_add_f32_dpp v90, v78, v78 row_mirror row_mask:0xf bank_mask:0xf bound_ctrl:1
	v_mul_f32_e32 v78, 0x3e38aa3b, v90
	v_max3_f32 v85, v85, v89, v78
	v_pk_mul_f32 v[78:79], v[8:9], v[104:105]
	s_lshl_b64 s[98:99], s[4:5], 2
	s_add_u32 s98, s98, s84
	s_addc_u32 s99, s99, s85
	s_add_u32 s98, s98, 0xc000
	s_addc_u32 s99, s99, 0
	global_load_dwordx4 v[102:105], v220, s[98:99] nt
	v_pk_mov_b32 v[82:83], v[80:81], v[78:79] op_sel:[1,0]
	v_mov_b32_e32 v81, v79
	v_pk_add_f32 v[78:79], v[82:83], v[80:81]
	s_waitcnt vmcnt(31)
	v_pk_mul_f32 v[80:81], v[6:7], v[106:107]
	v_add_f32_e32 v78, v78, v79
	s_nop 1
	v_add_f32_dpp v78, v78, v78 quad_perm:[1,0,3,2] row_mask:0xf bank_mask:0xf bound_ctrl:1
	s_nop 1
	v_add_f32_dpp v78, v78, v78 quad_perm:[2,3,0,1] row_mask:0xf bank_mask:0xf bound_ctrl:1
	s_nop 1
	v_add_f32_dpp v78, v78, v78 row_half_mirror row_mask:0xf bank_mask:0xf bound_ctrl:1
	s_nop 1
	v_add_f32_dpp v89, v78, v78 row_mirror row_mask:0xf bank_mask:0xf bound_ctrl:1
	v_pk_mul_f32 v[78:79], v[8:9], v[108:109]
	s_lshl_b64 s[98:99], s[4:5], 2
	s_add_u32 s98, s98, s84
	s_addc_u32 s99, s99, s85
	s_add_u32 s98, s98, 0xe000
	s_addc_u32 s99, s99, 0
	global_load_dwordx4 v[106:109], v220, s[98:99] nt
	v_mul_f32_e32 v91, 0x3e38aa3b, v89
	v_pk_mov_b32 v[82:83], v[80:81], v[78:79] op_sel:[1,0]
	v_mov_b32_e32 v81, v79
	v_pk_add_f32 v[78:79], v[82:83], v[80:81]
	s_waitcnt vmcnt(31)
	v_pk_mul_f32 v[80:81], v[6:7], v[110:111]
	v_add_f32_e32 v78, v78, v79
	s_nop 1
	v_add_f32_dpp v78, v78, v78 quad_perm:[1,0,3,2] row_mask:0xf bank_mask:0xf bound_ctrl:1
	s_nop 1
	v_add_f32_dpp v78, v78, v78 quad_perm:[2,3,0,1] row_mask:0xf bank_mask:0xf bound_ctrl:1
	s_nop 1
	v_add_f32_dpp v78, v78, v78 row_half_mirror row_mask:0xf bank_mask:0xf bound_ctrl:1
	s_nop 1
	v_add_f32_dpp v92, v78, v78 row_mirror row_mask:0xf bank_mask:0xf bound_ctrl:1
	v_mul_f32_e32 v78, 0x3e38aa3b, v92
	v_max3_f32 v85, v85, v91, v78
	v_pk_mul_f32 v[78:79], v[8:9], v[112:113]
	s_lshl_b64 s[98:99], s[4:5], 2
	s_add_u32 s98, s98, s84
	s_addc_u32 s99, s99, s85
	s_add_u32 s98, s98, 0x10000
	s_addc_u32 s99, s99, 0
	global_load_dwordx4 v[110:113], v220, s[98:99] nt
	v_pk_mov_b32 v[82:83], v[80:81], v[78:79] op_sel:[1,0]
	v_mov_b32_e32 v81, v79
	v_pk_add_f32 v[78:79], v[82:83], v[80:81]
	s_waitcnt vmcnt(31)
	v_pk_mul_f32 v[80:81], v[6:7], v[114:115]
	v_add_f32_e32 v78, v78, v79
	s_nop 1
	v_add_f32_dpp v78, v78, v78 quad_perm:[1,0,3,2] row_mask:0xf bank_mask:0xf bound_ctrl:1
	s_nop 1
	v_add_f32_dpp v78, v78, v78 quad_perm:[2,3,0,1] row_mask:0xf bank_mask:0xf bound_ctrl:1
	s_nop 1
	v_add_f32_dpp v78, v78, v78 row_half_mirror row_mask:0xf bank_mask:0xf bound_ctrl:1
	s_nop 1
	v_add_f32_dpp v91, v78, v78 row_mirror row_mask:0xf bank_mask:0xf bound_ctrl:1
	v_pk_mul_f32 v[78:79], v[8:9], v[116:117]
	s_lshl_b64 s[98:99], s[4:5], 2
	s_add_u32 s98, s98, s84
	s_addc_u32 s99, s99, s85
	s_add_u32 s98, s98, 0x12000
	s_addc_u32 s99, s99, 0
	global_load_dwordx4 v[114:117], v220, s[98:99] nt
	v_mul_f32_e32 v93, 0x3e38aa3b, v91
	v_pk_mov_b32 v[82:83], v[80:81], v[78:79] op_sel:[1,0]
	v_mov_b32_e32 v81, v79
	v_pk_add_f32 v[78:79], v[82:83], v[80:81]
	s_waitcnt vmcnt(31)
	v_pk_mul_f32 v[80:81], v[6:7], v[118:119]
	v_add_f32_e32 v78, v78, v79
	s_nop 1
	v_add_f32_dpp v78, v78, v78 quad_perm:[1,0,3,2] row_mask:0xf bank_mask:0xf bound_ctrl:1
	s_nop 1
	v_add_f32_dpp v78, v78, v78 quad_perm:[2,3,0,1] row_mask:0xf bank_mask:0xf bound_ctrl:1
	s_nop 1
	v_add_f32_dpp v78, v78, v78 row_half_mirror row_mask:0xf bank_mask:0xf bound_ctrl:1
	s_nop 1
	v_add_f32_dpp v94, v78, v78 row_mirror row_mask:0xf bank_mask:0xf bound_ctrl:1
	v_mul_f32_e32 v78, 0x3e38aa3b, v94
	v_max3_f32 v85, v85, v93, v78
	v_pk_mul_f32 v[78:79], v[8:9], v[120:121]
	s_lshl_b64 s[98:99], s[4:5], 2
	s_add_u32 s98, s98, s84
	s_addc_u32 s99, s99, s85
	s_add_u32 s98, s98, 0x14000
	s_addc_u32 s99, s99, 0
	global_load_dwordx4 v[118:121], v220, s[98:99] nt
	v_pk_mov_b32 v[82:83], v[80:81], v[78:79] op_sel:[1,0]
	v_mov_b32_e32 v81, v79
	v_pk_add_f32 v[78:79], v[82:83], v[80:81]
	s_waitcnt vmcnt(31)
	v_pk_mul_f32 v[80:81], v[6:7], v[122:123]
	v_add_f32_e32 v78, v78, v79
	s_nop 1
	v_add_f32_dpp v78, v78, v78 quad_perm:[1,0,3,2] row_mask:0xf bank_mask:0xf bound_ctrl:1
	s_nop 1
	v_add_f32_dpp v78, v78, v78 quad_perm:[2,3,0,1] row_mask:0xf bank_mask:0xf bound_ctrl:1
	s_nop 1
	v_add_f32_dpp v78, v78, v78 row_half_mirror row_mask:0xf bank_mask:0xf bound_ctrl:1
	s_nop 1
	v_add_f32_dpp v93, v78, v78 row_mirror row_mask:0xf bank_mask:0xf bound_ctrl:1
	v_pk_mul_f32 v[78:79], v[8:9], v[124:125]
	s_lshl_b64 s[98:99], s[4:5], 2
	s_add_u32 s98, s98, s84
	s_addc_u32 s99, s99, s85
	s_add_u32 s98, s98, 0x16000
	s_addc_u32 s99, s99, 0
	global_load_dwordx4 v[122:125], v220, s[98:99] nt
	v_mul_f32_e32 v95, 0x3e38aa3b, v93
	v_pk_mov_b32 v[82:83], v[80:81], v[78:79] op_sel:[1,0]
	v_mov_b32_e32 v81, v79
	v_pk_add_f32 v[78:79], v[82:83], v[80:81]
	s_waitcnt vmcnt(31)
	v_pk_mul_f32 v[80:81], v[6:7], v[126:127]
	v_add_f32_e32 v78, v78, v79
	s_nop 1
	v_add_f32_dpp v78, v78, v78 quad_perm:[1,0,3,2] row_mask:0xf bank_mask:0xf bound_ctrl:1
	s_nop 1
	v_add_f32_dpp v78, v78, v78 quad_perm:[2,3,0,1] row_mask:0xf bank_mask:0xf bound_ctrl:1
	s_nop 1
	v_add_f32_dpp v78, v78, v78 row_half_mirror row_mask:0xf bank_mask:0xf bound_ctrl:1
	s_nop 1
	v_add_f32_dpp v96, v78, v78 row_mirror row_mask:0xf bank_mask:0xf bound_ctrl:1
	v_mul_f32_e32 v78, 0x3e38aa3b, v96
	v_max3_f32 v85, v85, v95, v78
	v_pk_mul_f32 v[78:79], v[8:9], v[128:129]
	s_lshl_b64 s[98:99], s[4:5], 2
	s_add_u32 s98, s98, s84
	s_addc_u32 s99, s99, s85
	s_add_u32 s98, s98, 0x18000
	s_addc_u32 s99, s99, 0
	global_load_dwordx4 v[126:129], v220, s[98:99] nt
	v_pk_mov_b32 v[82:83], v[80:81], v[78:79] op_sel:[1,0]
	v_mov_b32_e32 v81, v79
	v_pk_add_f32 v[78:79], v[82:83], v[80:81]
	s_waitcnt vmcnt(31)
	v_pk_mul_f32 v[80:81], v[6:7], v[130:131]
	v_add_f32_e32 v78, v78, v79
	s_nop 1
	v_add_f32_dpp v78, v78, v78 quad_perm:[1,0,3,2] row_mask:0xf bank_mask:0xf bound_ctrl:1
	s_nop 1
	v_add_f32_dpp v78, v78, v78 quad_perm:[2,3,0,1] row_mask:0xf bank_mask:0xf bound_ctrl:1
	s_nop 1
	v_add_f32_dpp v78, v78, v78 row_half_mirror row_mask:0xf bank_mask:0xf bound_ctrl:1
	s_nop 1
	v_add_f32_dpp v95, v78, v78 row_mirror row_mask:0xf bank_mask:0xf bound_ctrl:1
	v_pk_mul_f32 v[78:79], v[8:9], v[132:133]
	s_lshl_b64 s[98:99], s[4:5], 2
	s_add_u32 s98, s98, s84
	s_addc_u32 s99, s99, s85
	s_add_u32 s98, s98, 0x1a000
	s_addc_u32 s99, s99, 0
	global_load_dwordx4 v[130:133], v220, s[98:99] nt
	v_mul_f32_e32 v97, 0x3e38aa3b, v95
	v_pk_mov_b32 v[82:83], v[80:81], v[78:79] op_sel:[1,0]
	v_mov_b32_e32 v81, v79
	v_pk_add_f32 v[78:79], v[82:83], v[80:81]
	s_waitcnt vmcnt(31)
	v_pk_mul_f32 v[80:81], v[6:7], v[134:135]
	v_add_f32_e32 v78, v78, v79
	s_nop 1
	v_add_f32_dpp v78, v78, v78 quad_perm:[1,0,3,2] row_mask:0xf bank_mask:0xf bound_ctrl:1
	s_nop 1
	v_add_f32_dpp v78, v78, v78 quad_perm:[2,3,0,1] row_mask:0xf bank_mask:0xf bound_ctrl:1
	s_nop 1
	v_add_f32_dpp v78, v78, v78 row_half_mirror row_mask:0xf bank_mask:0xf bound_ctrl:1
	s_nop 1
	v_add_f32_dpp v98, v78, v78 row_mirror row_mask:0xf bank_mask:0xf bound_ctrl:1
	v_mul_f32_e32 v78, 0x3e38aa3b, v98
	v_max3_f32 v85, v85, v97, v78
	v_pk_mul_f32 v[78:79], v[8:9], v[136:137]
	s_lshl_b64 s[98:99], s[4:5], 2
	s_add_u32 s98, s98, s84
	s_addc_u32 s99, s99, s85
	s_add_u32 s98, s98, 0x1c000
	s_addc_u32 s99, s99, 0
	global_load_dwordx4 v[134:137], v220, s[98:99] nt
	v_pk_mov_b32 v[82:83], v[80:81], v[78:79] op_sel:[1,0]
	v_mov_b32_e32 v81, v79
	v_pk_add_f32 v[78:79], v[82:83], v[80:81]
	s_waitcnt vmcnt(31)
	v_pk_mul_f32 v[80:81], v[6:7], v[138:139]
	v_add_f32_e32 v78, v78, v79
	s_nop 1
	v_add_f32_dpp v78, v78, v78 quad_perm:[1,0,3,2] row_mask:0xf bank_mask:0xf bound_ctrl:1
	s_nop 1
	v_add_f32_dpp v78, v78, v78 quad_perm:[2,3,0,1] row_mask:0xf bank_mask:0xf bound_ctrl:1
	s_nop 1
	v_add_f32_dpp v78, v78, v78 row_half_mirror row_mask:0xf bank_mask:0xf bound_ctrl:1
	s_nop 1
	v_add_f32_dpp v97, v78, v78 row_mirror row_mask:0xf bank_mask:0xf bound_ctrl:1
	v_pk_mul_f32 v[78:79], v[8:9], v[140:141]
	s_lshl_b64 s[98:99], s[4:5], 2
	s_add_u32 s98, s98, s84
	s_addc_u32 s99, s99, s85
	s_add_u32 s98, s98, 0x1e000
	s_addc_u32 s99, s99, 0
	global_load_dwordx4 v[138:141], v220, s[98:99] nt
	v_mul_f32_e32 v99, 0x3e38aa3b, v97
	v_pk_mov_b32 v[82:83], v[80:81], v[78:79] op_sel:[1,0]
	v_mov_b32_e32 v81, v79
	v_pk_add_f32 v[78:79], v[82:83], v[80:81]
	s_nop 0
	v_add_f32_e32 v78, v78, v79
	s_nop 1
	v_add_f32_dpp v78, v78, v78 quad_perm:[1,0,3,2] row_mask:0xf bank_mask:0xf bound_ctrl:1
	s_nop 1
	v_add_f32_dpp v78, v78, v78 quad_perm:[2,3,0,1] row_mask:0xf bank_mask:0xf bound_ctrl:1
	s_nop 1
	v_add_f32_dpp v78, v78, v78 row_half_mirror row_mask:0xf bank_mask:0xf bound_ctrl:1
	s_nop 1
	v_add_f32_dpp v79, v78, v78 row_mirror row_mask:0xf bank_mask:0xf bound_ctrl:1
	v_mul_f32_e32 v78, 0x3e38aa3b, v79
	v_max3_f32 v78, v85, v99, v78
	v_mov_b32_e32 v80, v78
	s_nop 1
	v_permlane16_swap_b32_e32 v78, v80
	v_max_f32_e32 v80, v80, v80
	v_max_f32_e32 v78, v78, v78
	v_max_f32_e32 v78, v78, v80
	v_mov_b32_e32 v80, v78
	s_nop 1
	v_permlane32_swap_b32_e32 v78, v80
	v_max3_f32 v157, v156, v78, v80
	v_fma_f32 v80, v154, s41, -v157
	v_sub_f32_e32 v78, v156, v157
	v_exp_f32_e32 v80, v80
	v_exp_f32_e32 v78, v78
	v_mov_b32_e32 v85, v80
	v_fmac_f32_e32 v85, v69, v78
	v_pk_mul_f32 v[82:83], v[144:145], v[80:81] op_sel_hi:[1,0]
	v_pk_mul_f32 v[80:81], v[142:143], v[80:81] op_sel_hi:[1,0]
	v_fma_f32 v69, v84, s41, -v157
	v_pk_fma_f32 v[74:75], v[74:75], v[78:79], v[80:81] op_sel_hi:[1,0,1]
	v_pk_fma_f32 v[72:73], v[72:73], v[78:79], v[82:83] op_sel_hi:[1,0,1]
	v_exp_f32_e32 v78, v69
	s_nop 0
	v_add_f32_e32 v69, v78, v85
	v_pk_fma_f32 v[72:73], v[148:149], v[78:79], v[72:73] op_sel_hi:[1,0,1]
	v_pk_fma_f32 v[74:75], v[146:147], v[78:79], v[74:75] op_sel_hi:[1,0,1]
	v_fma_f32 v78, v86, s41, -v157
	v_exp_f32_e32 v78, v78
	s_nop 0
	v_add_f32_e32 v69, v78, v69
	v_pk_fma_f32 v[74:75], v[150:151], v[78:79], v[74:75] op_sel_hi:[1,0,1]
	v_pk_fma_f32 v[72:73], v[152:153], v[78:79], v[72:73] op_sel_hi:[1,0,1]
	v_fma_f32 v78, v88, s41, -v157
	v_exp_f32_e32 v78, v78
	s_nop 0
	v_pk_fma_f32 v[64:65], v[64:65], v[78:79], v[72:73] op_sel_hi:[1,0,1]
	v_fma_f32 v72, v87, s41, -v157
	v_exp_f32_e32 v72, v72
	v_pk_fma_f32 v[62:63], v[62:63], v[78:79], v[74:75] op_sel_hi:[1,0,1]
	v_add_f32_e32 v69, v78, v69
	v_pk_fma_f32 v[58:59], v[58:59], v[72:73], v[62:63] op_sel_hi:[1,0,1]
	v_fma_f32 v62, v90, s41, -v157
	v_exp_f32_e32 v62, v62
	v_add_f32_e32 v69, v72, v69
	v_pk_fma_f32 v[60:61], v[60:61], v[72:73], v[64:65] op_sel_hi:[1,0,1]
	v_add_f32_e32 v63, v62, v69
	v_pk_fma_f32 v[54:55], v[54:55], v[62:63], v[58:59] op_sel_hi:[1,0,1]
	v_fma_f32 v58, v89, s41, -v157
	v_exp_f32_e32 v58, v58
	v_pk_fma_f32 v[56:57], v[56:57], v[62:63], v[60:61] op_sel_hi:[1,0,1]
	v_add_f32_e32 v59, v58, v63
	v_pk_fma_f32 v[50:51], v[50:51], v[58:59], v[54:55] op_sel_hi:[1,0,1]
	v_fma_f32 v54, v92, s41, -v157
	v_exp_f32_e32 v54, v54
	v_pk_fma_f32 v[52:53], v[52:53], v[58:59], v[56:57] op_sel_hi:[1,0,1]
	v_add_f32_e32 v55, v54, v59
	v_pk_fma_f32 v[46:47], v[46:47], v[54:55], v[50:51] op_sel_hi:[1,0,1]
	v_fma_f32 v50, v91, s41, -v157
	v_exp_f32_e32 v50, v50
	v_pk_fma_f32 v[48:49], v[48:49], v[54:55], v[52:53] op_sel_hi:[1,0,1]
	v_add_f32_e32 v51, v50, v55
	v_pk_fma_f32 v[42:43], v[42:43], v[50:51], v[46:47] op_sel_hi:[1,0,1]
	v_fma_f32 v46, v94, s41, -v157
	v_exp_f32_e32 v46, v46
	v_pk_fma_f32 v[44:45], v[44:45], v[50:51], v[48:49] op_sel_hi:[1,0,1]
	v_add_f32_e32 v47, v46, v51
	v_pk_fma_f32 v[38:39], v[38:39], v[46:47], v[42:43] op_sel_hi:[1,0,1]
	v_fma_f32 v42, v93, s41, -v157
	v_exp_f32_e32 v42, v42
	v_pk_fma_f32 v[40:41], v[40:41], v[46:47], v[44:45] op_sel_hi:[1,0,1]
	v_add_f32_e32 v43, v42, v47
	v_pk_fma_f32 v[34:35], v[34:35], v[42:43], v[38:39] op_sel_hi:[1,0,1]
	v_fma_f32 v38, v96, s41, -v157
	v_exp_f32_e32 v38, v38
	v_pk_fma_f32 v[36:37], v[36:37], v[42:43], v[40:41] op_sel_hi:[1,0,1]
	v_add_f32_e32 v39, v38, v43
	v_pk_fma_f32 v[30:31], v[30:31], v[38:39], v[34:35] op_sel_hi:[1,0,1]
	v_fma_f32 v34, v95, s41, -v157
	v_exp_f32_e32 v34, v34
	v_pk_fma_f32 v[32:33], v[32:33], v[38:39], v[36:37] op_sel_hi:[1,0,1]
	v_add_f32_e32 v35, v34, v39
	v_pk_fma_f32 v[26:27], v[26:27], v[34:35], v[30:31] op_sel_hi:[1,0,1]
	v_fma_f32 v30, v98, s41, -v157
	v_exp_f32_e32 v30, v30
	v_pk_fma_f32 v[28:29], v[28:29], v[34:35], v[32:33] op_sel_hi:[1,0,1]
	v_add_f32_e32 v31, v30, v35
	v_pk_fma_f32 v[22:23], v[22:23], v[30:31], v[26:27] op_sel_hi:[1,0,1]
	v_fma_f32 v26, v97, s41, -v157
	v_exp_f32_e32 v26, v26
	v_pk_fma_f32 v[24:25], v[24:25], v[30:31], v[28:29] op_sel_hi:[1,0,1]
	v_add_f32_e32 v27, v26, v31
	v_pk_fma_f32 v[18:19], v[18:19], v[26:27], v[22:23] op_sel_hi:[1,0,1]
	v_fma_f32 v22, v79, s41, -v157
	s_waitcnt vmcnt(31)
	v_mov_b64_e32 v[78:79], v[158:159]
	v_mov_b64_e32 v[80:81], v[160:161]
	s_waitcnt vmcnt(30)
	v_mov_b64_e32 v[82:83], v[162:163]
	v_mov_b64_e32 v[84:85], v[164:165]
	s_waitcnt vmcnt(29)
	v_mov_b64_e32 v[86:87], v[166:167]
	v_mov_b64_e32 v[88:89], v[168:169]
	s_waitcnt vmcnt(28)
	v_mov_b64_e32 v[90:91], v[170:171]
	v_mov_b64_e32 v[92:93], v[172:173]
	s_waitcnt vmcnt(27)
	v_mov_b64_e32 v[94:95], v[174:175]
	v_mov_b64_e32 v[96:97], v[176:177]
	s_waitcnt vmcnt(26)
	v_mov_b64_e32 v[98:99], v[178:179]
	v_mov_b64_e32 v[100:101], v[180:181]
	s_waitcnt vmcnt(25)
	v_mov_b64_e32 v[142:143], v[182:183]
	v_mov_b64_e32 v[144:145], v[184:185]
	s_waitcnt vmcnt(24)
	v_mov_b64_e32 v[146:147], v[186:187]
	v_mov_b64_e32 v[148:149], v[188:189]
	s_waitcnt vmcnt(23)
	v_mov_b64_e32 v[150:151], v[192:193]
	v_mov_b64_e32 v[152:153], v[194:195]
	s_waitcnt vmcnt(22)
	v_mov_b64_e32 v[62:63], v[196:197]
	v_mov_b64_e32 v[64:65], v[198:199]
	s_waitcnt vmcnt(21)
	v_mov_b64_e32 v[58:59], v[200:201]
	v_mov_b64_e32 v[60:61], v[202:203]
	s_waitcnt vmcnt(20)
	v_mov_b64_e32 v[54:55], v[204:205]
	v_mov_b64_e32 v[56:57], v[206:207]
	s_waitcnt vmcnt(19)
	v_mov_b64_e32 v[50:51], v[208:209]
	v_mov_b64_e32 v[52:53], v[210:211]
	s_waitcnt vmcnt(18)
	v_mov_b64_e32 v[46:47], v[212:213]
	v_mov_b64_e32 v[48:49], v[214:215]
	s_waitcnt vmcnt(17)
	v_mov_b64_e32 v[42:43], v[216:217]
	v_mov_b64_e32 v[44:45], v[218:219]
	s_waitcnt vmcnt(16)
	v_mov_b64_e32 v[38:39], v[224:225]
	v_mov_b64_e32 v[40:41], v[226:227]
	s_waitcnt vmcnt(15)
	v_mov_b64_e32 v[34:35], v[228:229]
	v_mov_b64_e32 v[36:37], v[230:231]
	s_waitcnt vmcnt(14)
	v_mov_b64_e32 v[30:31], v[232:233]
	v_mov_b64_e32 v[32:33], v[234:235]
	v_exp_f32_e32 v22, v22
	v_pk_fma_f32 v[20:21], v[20:21], v[26:27], v[24:25] op_sel_hi:[1,0,1]
	v_pk_fma_f32 v[74:75], v[14:15], v[22:23], v[18:19] op_sel_hi:[1,0,1]
	v_pk_fma_f32 v[72:73], v[16:17], v[22:23], v[20:21] op_sel_hi:[1,0,1]
	s_waitcnt vmcnt(11)
	v_mov_b64_e32 v[18:19], v[244:245]
	v_mov_b64_e32 v[20:21], v[246:247]
	s_waitcnt vmcnt(10)
	v_mov_b64_e32 v[14:15], v[252:253]
	v_mov_b64_e32 v[16:17], v[254:255]
	v_add_f32_e32 v69, v22, v27
	v_mov_b64_e32 v[26:27], v[236:237]
	v_mov_b64_e32 v[28:29], v[238:239]
	v_mov_b64_e32 v[22:23], v[240:241]
	v_mov_b64_e32 v[24:25], v[242:243]
	s_lshl_b64 s[98:99], s[4:5], 2
	s_add_u32 s98, s98, s84
	s_addc_u32 s99, s99, s85
	s_add_u32 s98, s98, 0x20000
	s_addc_u32 s99, s99, 0
	global_load_dwordx4 v[158:161], v220, s[98:99] nt
	s_lshl_b64 s[98:99], s[4:5], 2
	s_add_u32 s98, s98, s84
	s_addc_u32 s99, s99, s85
	s_add_u32 s98, s98, 0x22000
	s_addc_u32 s99, s99, 0
	global_load_dwordx4 v[162:165], v220, s[98:99] nt
	s_lshl_b64 s[98:99], s[4:5], 2
	s_add_u32 s98, s98, s84
	s_addc_u32 s99, s99, s85
	s_add_u32 s98, s98, 0x24000
	s_addc_u32 s99, s99, 0
	global_load_dwordx4 v[166:169], v220, s[98:99] nt
	s_lshl_b64 s[98:99], s[4:5], 2
	s_add_u32 s98, s98, s84
	s_addc_u32 s99, s99, s85
	s_add_u32 s98, s98, 0x26000
	s_addc_u32 s99, s99, 0
	global_load_dwordx4 v[170:173], v220, s[98:99] nt
	s_lshl_b64 s[98:99], s[4:5], 2
	s_add_u32 s98, s98, s84
	s_addc_u32 s99, s99, s85
	s_add_u32 s98, s98, 0x28000
	s_addc_u32 s99, s99, 0
	global_load_dwordx4 v[174:177], v220, s[98:99] nt
	s_lshl_b64 s[98:99], s[4:5], 2
	s_add_u32 s98, s98, s84
	s_addc_u32 s99, s99, s85
	s_add_u32 s98, s98, 0x2a000
	s_addc_u32 s99, s99, 0
	global_load_dwordx4 v[178:181], v220, s[98:99] nt
	s_lshl_b64 s[98:99], s[4:5], 2
	s_add_u32 s98, s98, s86
	s_addc_u32 s99, s99, s87
	s_add_u32 s98, s98, 0x20000
	s_addc_u32 s99, s99, 0
	global_load_dwordx4 v[182:185], v220, s[98:99] nt
	s_lshl_b64 s[98:99], s[4:5], 2
	s_add_u32 s98, s98, s86
	s_addc_u32 s99, s99, s87
	s_add_u32 s98, s98, 0x22000
	s_addc_u32 s99, s99, 0
	global_load_dwordx4 v[186:189], v220, s[98:99] nt
	s_lshl_b64 s[98:99], s[4:5], 2
	s_add_u32 s98, s98, s86
	s_addc_u32 s99, s99, s87
	s_add_u32 s98, s98, 0x24000
	s_addc_u32 s99, s99, 0
	global_load_dwordx4 v[192:195], v220, s[98:99] nt
	s_lshl_b64 s[98:99], s[4:5], 2
	s_add_u32 s98, s98, s86
	s_addc_u32 s99, s99, s87
	s_add_u32 s98, s98, 0x26000
	s_addc_u32 s99, s99, 0
	global_load_dwordx4 v[196:199], v220, s[98:99] nt
	s_lshl_b64 s[98:99], s[4:5], 2
	s_add_u32 s98, s98, s86
	s_addc_u32 s99, s99, s87
	s_add_u32 s98, s98, 0x28000
	s_addc_u32 s99, s99, 0
	global_load_dwordx4 v[200:203], v220, s[98:99] nt
	s_lshl_b64 s[98:99], s[4:5], 2
	s_add_u32 s98, s98, s86
	s_addc_u32 s99, s99, s87
	s_add_u32 s98, s98, 0x2a000
	s_addc_u32 s99, s99, 0
	global_load_dwordx4 v[204:207], v220, s[98:99] nt
	s_lshl_b64 s[98:99], s[4:5], 2
	s_add_u32 s98, s98, s86
	s_addc_u32 s99, s99, s87
	s_add_u32 s98, s98, 0x2c000
	s_addc_u32 s99, s99, 0
	global_load_dwordx4 v[208:211], v220, s[98:99] nt
	s_lshl_b64 s[98:99], s[4:5], 2
	s_add_u32 s98, s98, s86
	s_addc_u32 s99, s99, s87
	s_add_u32 s98, s98, 0x2e000
	s_addc_u32 s99, s99, 0
	global_load_dwordx4 v[212:215], v220, s[98:99] nt
	s_lshl_b64 s[98:99], s[4:5], 2
	s_add_u32 s98, s98, s86
	s_addc_u32 s99, s99, s87
	s_add_u32 s98, s98, 0x30000
	s_addc_u32 s99, s99, 0
	global_load_dwordx4 v[216:219], v220, s[98:99] nt
	s_lshl_b64 s[98:99], s[4:5], 2
	s_add_u32 s98, s98, s86
	s_addc_u32 s99, s99, s87
	s_add_u32 s98, s98, 0x32000
	s_addc_u32 s99, s99, 0
	global_load_dwordx4 v[224:227], v220, s[98:99] nt
	s_lshl_b64 s[98:99], s[4:5], 2
	s_add_u32 s98, s98, s86
	s_addc_u32 s99, s99, s87
	s_add_u32 s98, s98, 0x34000
	s_addc_u32 s99, s99, 0
	global_load_dwordx4 v[228:231], v220, s[98:99] nt
	s_lshl_b64 s[98:99], s[4:5], 2
	s_add_u32 s98, s98, s86
	s_addc_u32 s99, s99, s87
	s_add_u32 s98, s98, 0x36000
	s_addc_u32 s99, s99, 0
	global_load_dwordx4 v[232:235], v220, s[98:99] nt
	s_lshl_b64 s[98:99], s[4:5], 2
	s_add_u32 s98, s98, s86
	s_addc_u32 s99, s99, s87
	s_add_u32 s98, s98, 0x38000
	s_addc_u32 s99, s99, 0
	global_load_dwordx4 v[236:239], v220, s[98:99] nt
	s_lshl_b64 s[98:99], s[4:5], 2
	s_add_u32 s98, s98, s86
	s_addc_u32 s99, s99, s87
	s_add_u32 s98, s98, 0x3a000
	s_addc_u32 s99, s99, 0
	global_load_dwordx4 v[240:243], v220, s[98:99] nt
	s_lshl_b64 s[98:99], s[4:5], 2
	s_add_u32 s98, s98, s86
	s_addc_u32 s99, s99, s87
	s_add_u32 s98, s98, 0x3c000
	s_addc_u32 s99, s99, 0
	global_load_dwordx4 v[244:247], v220, s[98:99] nt
	s_lshl_b64 s[98:99], s[4:5], 2
	s_add_u32 s98, s98, s86
	s_addc_u32 s99, s99, s87
	s_add_u32 s98, s98, 0x3e000
	s_addc_u32 s99, s99, 0
	global_load_dwordx4 v[252:255], v220, s[98:99] nt
	v_pk_mul_f32 v[80:81], v[8:9], v[80:81]
	v_pk_mul_f32 v[78:79], v[6:7], v[78:79]
	s_nop 0
	v_pk_mov_b32 v[154:155], v[78:79], v[80:81] op_sel:[1,0]
	v_mov_b32_e32 v79, v81
	v_pk_add_f32 v[78:79], v[154:155], v[78:79]
	s_nop 0
	v_add_f32_e32 v78, v78, v79
	s_nop 1
	v_add_f32_dpp v78, v78, v78 quad_perm:[1,0,3,2] row_mask:0xf bank_mask:0xf bound_ctrl:1
	s_nop 1
	v_add_f32_dpp v78, v78, v78 quad_perm:[2,3,0,1] row_mask:0xf bank_mask:0xf bound_ctrl:1
	s_nop 1
	v_add_f32_dpp v78, v78, v78 row_half_mirror row_mask:0xf bank_mask:0xf bound_ctrl:1
	v_pk_mul_f32 v[80:81], v[6:7], v[82:83]
	s_nop 0
	v_add_f32_dpp v154, v78, v78 row_mirror row_mask:0xf bank_mask:0xf bound_ctrl:1
	v_pk_mul_f32 v[78:79], v[8:9], v[84:85]
	s_nop 0
	v_pk_mov_b32 v[82:83], v[80:81], v[78:79] op_sel:[1,0]
	v_mov_b32_e32 v81, v79
	v_pk_add_f32 v[78:79], v[82:83], v[80:81]
	s_nop 0
	v_add_f32_e32 v78, v78, v79
	v_mul_f32_e32 v155, 0x3e38aa3b, v154
	s_nop 0
	v_add_f32_dpp v78, v78, v78 quad_perm:[1,0,3,2] row_mask:0xf bank_mask:0xf bound_ctrl:1
	v_pk_mul_f32 v[80:81], v[6:7], v[86:87]
	s_nop 0
	v_add_f32_dpp v78, v78, v78 quad_perm:[2,3,0,1] row_mask:0xf bank_mask:0xf bound_ctrl:1
	s_nop 1
	v_add_f32_dpp v78, v78, v78 row_half_mirror row_mask:0xf bank_mask:0xf bound_ctrl:1
	s_nop 1
	v_add_f32_dpp v84, v78, v78 row_mirror row_mask:0xf bank_mask:0xf bound_ctrl:1
	v_mul_f32_e32 v78, 0x3e38aa3b, v84
	v_max3_f32 v85, v155, s42, v78
	v_pk_mul_f32 v[78:79], v[8:9], v[88:89]
	s_nop 0
	v_pk_mov_b32 v[82:83], v[80:81], v[78:79] op_sel:[1,0]
	v_mov_b32_e32 v81, v79
	v_pk_add_f32 v[78:79], v[82:83], v[80:81]
	v_pk_mul_f32 v[80:81], v[6:7], v[90:91]
	v_add_f32_e32 v78, v78, v79
	s_nop 1
	v_add_f32_dpp v78, v78, v78 quad_perm:[1,0,3,2] row_mask:0xf bank_mask:0xf bound_ctrl:1
	s_nop 1
	v_add_f32_dpp v78, v78, v78 quad_perm:[2,3,0,1] row_mask:0xf bank_mask:0xf bound_ctrl:1
	s_nop 1
	v_add_f32_dpp v78, v78, v78 row_half_mirror row_mask:0xf bank_mask:0xf bound_ctrl:1
	s_nop 1
	v_add_f32_dpp v86, v78, v78 row_mirror row_mask:0xf bank_mask:0xf bound_ctrl:1
	v_pk_mul_f32 v[78:79], v[8:9], v[92:93]
	v_mul_f32_e32 v87, 0x3e38aa3b, v86
	v_pk_mov_b32 v[82:83], v[80:81], v[78:79] op_sel:[1,0]
	v_mov_b32_e32 v81, v79
	v_pk_add_f32 v[78:79], v[82:83], v[80:81]
	v_pk_mul_f32 v[80:81], v[6:7], v[94:95]
	v_add_f32_e32 v78, v78, v79
	s_nop 1
	v_add_f32_dpp v78, v78, v78 quad_perm:[1,0,3,2] row_mask:0xf bank_mask:0xf bound_ctrl:1
	s_nop 1
	v_add_f32_dpp v78, v78, v78 quad_perm:[2,3,0,1] row_mask:0xf bank_mask:0xf bound_ctrl:1
	s_nop 1
	v_add_f32_dpp v78, v78, v78 row_half_mirror row_mask:0xf bank_mask:0xf bound_ctrl:1
	s_nop 1
	v_add_f32_dpp v88, v78, v78 row_mirror row_mask:0xf bank_mask:0xf bound_ctrl:1
	v_mul_f32_e32 v78, 0x3e38aa3b, v88
	v_max3_f32 v85, v85, v87, v78
	v_pk_mul_f32 v[78:79], v[8:9], v[96:97]
	s_nop 0
	v_pk_mov_b32 v[82:83], v[80:81], v[78:79] op_sel:[1,0]
	v_mov_b32_e32 v81, v79
	v_pk_add_f32 v[78:79], v[82:83], v[80:81]
	v_pk_mul_f32 v[80:81], v[6:7], v[98:99]
	v_add_f32_e32 v78, v78, v79
	s_nop 1
	v_add_f32_dpp v78, v78, v78 quad_perm:[1,0,3,2] row_mask:0xf bank_mask:0xf bound_ctrl:1
	s_nop 1
	v_add_f32_dpp v78, v78, v78 quad_perm:[2,3,0,1] row_mask:0xf bank_mask:0xf bound_ctrl:1
	s_nop 1
	v_add_f32_dpp v78, v78, v78 row_half_mirror row_mask:0xf bank_mask:0xf bound_ctrl:1
	s_nop 1
	v_add_f32_dpp v87, v78, v78 row_mirror row_mask:0xf bank_mask:0xf bound_ctrl:1
	v_pk_mul_f32 v[78:79], v[8:9], v[100:101]
	v_mul_f32_e32 v89, 0x3e38aa3b, v87
	v_pk_mov_b32 v[82:83], v[80:81], v[78:79] op_sel:[1,0]
	v_mov_b32_e32 v81, v79
	v_pk_add_f32 v[78:79], v[82:83], v[80:81]
	s_waitcnt vmcnt(31)
	v_pk_mul_f32 v[80:81], v[6:7], v[102:103]
	v_add_f32_e32 v78, v78, v79
	s_nop 1
	v_add_f32_dpp v78, v78, v78 quad_perm:[1,0,3,2] row_mask:0xf bank_mask:0xf bound_ctrl:1
	s_nop 1
	v_add_f32_dpp v78, v78, v78 quad_perm:[2,3,0,1] row_mask:0xf bank_mask:0xf bound_ctrl:1
	s_nop 1
	v_add_f32_dpp v78, v78, v78 row_half_mirror row_mask:0xf bank_mask:0xf bound_ctrl:1
	s_nop 1
	v_add_f32_dpp v90, v78, v78 row_mirror row_mask:0xf bank_mask:0xf bound_ctrl:1
	v_mul_f32_e32 v78, 0x3e38aa3b, v90
	v_max3_f32 v85, v85, v89, v78
	v_pk_mul_f32 v[78:79], v[8:9], v[104:105]
	s_lshl_b64 s[98:99], s[4:5], 2
	s_add_u32 s98, s98, s84
	s_addc_u32 s99, s99, s85
	s_add_u32 s98, s98, 0x2c000
	s_addc_u32 s99, s99, 0
	global_load_dwordx4 v[102:105], v220, s[98:99] nt
	v_pk_mov_b32 v[82:83], v[80:81], v[78:79] op_sel:[1,0]
	v_mov_b32_e32 v81, v79
	v_pk_add_f32 v[78:79], v[82:83], v[80:81]
	s_waitcnt vmcnt(31)
	v_pk_mul_f32 v[80:81], v[6:7], v[106:107]
	v_add_f32_e32 v78, v78, v79
	s_nop 1
	v_add_f32_dpp v78, v78, v78 quad_perm:[1,0,3,2] row_mask:0xf bank_mask:0xf bound_ctrl:1
	s_nop 1
	v_add_f32_dpp v78, v78, v78 quad_perm:[2,3,0,1] row_mask:0xf bank_mask:0xf bound_ctrl:1
	s_nop 1
	v_add_f32_dpp v78, v78, v78 row_half_mirror row_mask:0xf bank_mask:0xf bound_ctrl:1
	s_nop 1
	v_add_f32_dpp v89, v78, v78 row_mirror row_mask:0xf bank_mask:0xf bound_ctrl:1
	v_pk_mul_f32 v[78:79], v[8:9], v[108:109]
	s_lshl_b64 s[98:99], s[4:5], 2
	s_add_u32 s98, s98, s84
	s_addc_u32 s99, s99, s85
	s_add_u32 s98, s98, 0x2e000
	s_addc_u32 s99, s99, 0
	global_load_dwordx4 v[106:109], v220, s[98:99] nt
	v_mul_f32_e32 v91, 0x3e38aa3b, v89
	v_pk_mov_b32 v[82:83], v[80:81], v[78:79] op_sel:[1,0]
	v_mov_b32_e32 v81, v79
	v_pk_add_f32 v[78:79], v[82:83], v[80:81]
	s_waitcnt vmcnt(31)
	v_pk_mul_f32 v[80:81], v[6:7], v[110:111]
	v_add_f32_e32 v78, v78, v79
	s_nop 1
	v_add_f32_dpp v78, v78, v78 quad_perm:[1,0,3,2] row_mask:0xf bank_mask:0xf bound_ctrl:1
	s_nop 1
	v_add_f32_dpp v78, v78, v78 quad_perm:[2,3,0,1] row_mask:0xf bank_mask:0xf bound_ctrl:1
	s_nop 1
	v_add_f32_dpp v78, v78, v78 row_half_mirror row_mask:0xf bank_mask:0xf bound_ctrl:1
	s_nop 1
	v_add_f32_dpp v92, v78, v78 row_mirror row_mask:0xf bank_mask:0xf bound_ctrl:1
	v_mul_f32_e32 v78, 0x3e38aa3b, v92
	v_max3_f32 v85, v85, v91, v78
	v_pk_mul_f32 v[78:79], v[8:9], v[112:113]
	s_lshl_b64 s[98:99], s[4:5], 2
	s_add_u32 s98, s98, s84
	s_addc_u32 s99, s99, s85
	s_add_u32 s98, s98, 0x30000
	s_addc_u32 s99, s99, 0
	global_load_dwordx4 v[110:113], v220, s[98:99] nt
	v_pk_mov_b32 v[82:83], v[80:81], v[78:79] op_sel:[1,0]
	v_mov_b32_e32 v81, v79
	v_pk_add_f32 v[78:79], v[82:83], v[80:81]
	s_waitcnt vmcnt(31)
	v_pk_mul_f32 v[80:81], v[6:7], v[114:115]
	v_add_f32_e32 v78, v78, v79
	s_nop 1
	v_add_f32_dpp v78, v78, v78 quad_perm:[1,0,3,2] row_mask:0xf bank_mask:0xf bound_ctrl:1
	s_nop 1
	v_add_f32_dpp v78, v78, v78 quad_perm:[2,3,0,1] row_mask:0xf bank_mask:0xf bound_ctrl:1
	s_nop 1
	v_add_f32_dpp v78, v78, v78 row_half_mirror row_mask:0xf bank_mask:0xf bound_ctrl:1
	s_nop 1
	v_add_f32_dpp v91, v78, v78 row_mirror row_mask:0xf bank_mask:0xf bound_ctrl:1
	v_pk_mul_f32 v[78:79], v[8:9], v[116:117]
	s_lshl_b64 s[98:99], s[4:5], 2
	s_add_u32 s98, s98, s84
	s_addc_u32 s99, s99, s85
	s_add_u32 s98, s98, 0x32000
	s_addc_u32 s99, s99, 0
	global_load_dwordx4 v[114:117], v220, s[98:99] nt
	v_mul_f32_e32 v93, 0x3e38aa3b, v91
	v_pk_mov_b32 v[82:83], v[80:81], v[78:79] op_sel:[1,0]
	v_mov_b32_e32 v81, v79
	v_pk_add_f32 v[78:79], v[82:83], v[80:81]
	s_waitcnt vmcnt(31)
	v_pk_mul_f32 v[80:81], v[6:7], v[118:119]
	v_add_f32_e32 v78, v78, v79
	s_nop 1
	v_add_f32_dpp v78, v78, v78 quad_perm:[1,0,3,2] row_mask:0xf bank_mask:0xf bound_ctrl:1
	s_nop 1
	v_add_f32_dpp v78, v78, v78 quad_perm:[2,3,0,1] row_mask:0xf bank_mask:0xf bound_ctrl:1
	s_nop 1
	v_add_f32_dpp v78, v78, v78 row_half_mirror row_mask:0xf bank_mask:0xf bound_ctrl:1
	s_nop 1
	v_add_f32_dpp v94, v78, v78 row_mirror row_mask:0xf bank_mask:0xf bound_ctrl:1
	v_mul_f32_e32 v78, 0x3e38aa3b, v94
	v_max3_f32 v85, v85, v93, v78
	v_pk_mul_f32 v[78:79], v[8:9], v[120:121]
	s_lshl_b64 s[98:99], s[4:5], 2
	s_add_u32 s98, s98, s84
	s_addc_u32 s99, s99, s85
	s_add_u32 s98, s98, 0x34000
	s_addc_u32 s99, s99, 0
	global_load_dwordx4 v[118:121], v220, s[98:99] nt
	v_pk_mov_b32 v[82:83], v[80:81], v[78:79] op_sel:[1,0]
	v_mov_b32_e32 v81, v79
	v_pk_add_f32 v[78:79], v[82:83], v[80:81]
	s_waitcnt vmcnt(31)
	v_pk_mul_f32 v[80:81], v[6:7], v[122:123]
	v_add_f32_e32 v78, v78, v79
	s_nop 1
	v_add_f32_dpp v78, v78, v78 quad_perm:[1,0,3,2] row_mask:0xf bank_mask:0xf bound_ctrl:1
	s_nop 1
	v_add_f32_dpp v78, v78, v78 quad_perm:[2,3,0,1] row_mask:0xf bank_mask:0xf bound_ctrl:1
	s_nop 1
	v_add_f32_dpp v78, v78, v78 row_half_mirror row_mask:0xf bank_mask:0xf bound_ctrl:1
	s_nop 1
	v_add_f32_dpp v93, v78, v78 row_mirror row_mask:0xf bank_mask:0xf bound_ctrl:1
	v_pk_mul_f32 v[78:79], v[8:9], v[124:125]
	s_lshl_b64 s[98:99], s[4:5], 2
	s_add_u32 s98, s98, s84
	s_addc_u32 s99, s99, s85
	s_add_u32 s98, s98, 0x36000
	s_addc_u32 s99, s99, 0
	global_load_dwordx4 v[122:125], v220, s[98:99] nt
	v_mul_f32_e32 v95, 0x3e38aa3b, v93
	v_pk_mov_b32 v[82:83], v[80:81], v[78:79] op_sel:[1,0]
	v_mov_b32_e32 v81, v79
	v_pk_add_f32 v[78:79], v[82:83], v[80:81]
	s_waitcnt vmcnt(31)
	v_pk_mul_f32 v[80:81], v[6:7], v[126:127]
	v_add_f32_e32 v78, v78, v79
	s_nop 1
	v_add_f32_dpp v78, v78, v78 quad_perm:[1,0,3,2] row_mask:0xf bank_mask:0xf bound_ctrl:1
	s_nop 1
	v_add_f32_dpp v78, v78, v78 quad_perm:[2,3,0,1] row_mask:0xf bank_mask:0xf bound_ctrl:1
	s_nop 1
	v_add_f32_dpp v78, v78, v78 row_half_mirror row_mask:0xf bank_mask:0xf bound_ctrl:1
	s_nop 1
	v_add_f32_dpp v96, v78, v78 row_mirror row_mask:0xf bank_mask:0xf bound_ctrl:1
	v_mul_f32_e32 v78, 0x3e38aa3b, v96
	v_max3_f32 v85, v85, v95, v78
	v_pk_mul_f32 v[78:79], v[8:9], v[128:129]
	s_lshl_b64 s[98:99], s[4:5], 2
	s_add_u32 s98, s98, s84
	s_addc_u32 s99, s99, s85
	s_add_u32 s98, s98, 0x38000
	s_addc_u32 s99, s99, 0
	global_load_dwordx4 v[126:129], v220, s[98:99] nt
	v_pk_mov_b32 v[82:83], v[80:81], v[78:79] op_sel:[1,0]
	v_mov_b32_e32 v81, v79
	v_pk_add_f32 v[78:79], v[82:83], v[80:81]
	s_waitcnt vmcnt(31)
	v_pk_mul_f32 v[80:81], v[6:7], v[130:131]
	v_add_f32_e32 v78, v78, v79
	s_nop 1
	v_add_f32_dpp v78, v78, v78 quad_perm:[1,0,3,2] row_mask:0xf bank_mask:0xf bound_ctrl:1
	s_nop 1
	v_add_f32_dpp v78, v78, v78 quad_perm:[2,3,0,1] row_mask:0xf bank_mask:0xf bound_ctrl:1
	s_nop 1
	v_add_f32_dpp v78, v78, v78 row_half_mirror row_mask:0xf bank_mask:0xf bound_ctrl:1
	s_nop 1
	v_add_f32_dpp v95, v78, v78 row_mirror row_mask:0xf bank_mask:0xf bound_ctrl:1
	v_pk_mul_f32 v[78:79], v[8:9], v[132:133]
	s_lshl_b64 s[98:99], s[4:5], 2
	s_add_u32 s98, s98, s84
	s_addc_u32 s99, s99, s85
	s_add_u32 s98, s98, 0x3a000
	s_addc_u32 s99, s99, 0
	global_load_dwordx4 v[130:133], v220, s[98:99] nt
	v_mul_f32_e32 v97, 0x3e38aa3b, v95
	v_pk_mov_b32 v[82:83], v[80:81], v[78:79] op_sel:[1,0]
	v_mov_b32_e32 v81, v79
	v_pk_add_f32 v[78:79], v[82:83], v[80:81]
	s_waitcnt vmcnt(31)
	v_pk_mul_f32 v[80:81], v[6:7], v[134:135]
	v_add_f32_e32 v78, v78, v79
	s_nop 1
	v_add_f32_dpp v78, v78, v78 quad_perm:[1,0,3,2] row_mask:0xf bank_mask:0xf bound_ctrl:1
	s_nop 1
	v_add_f32_dpp v78, v78, v78 quad_perm:[2,3,0,1] row_mask:0xf bank_mask:0xf bound_ctrl:1
	s_nop 1
	v_add_f32_dpp v78, v78, v78 row_half_mirror row_mask:0xf bank_mask:0xf bound_ctrl:1
	s_nop 1
	v_add_f32_dpp v98, v78, v78 row_mirror row_mask:0xf bank_mask:0xf bound_ctrl:1
	v_mul_f32_e32 v78, 0x3e38aa3b, v98
	v_max3_f32 v85, v85, v97, v78
	v_pk_mul_f32 v[78:79], v[8:9], v[136:137]
	s_lshl_b64 s[98:99], s[4:5], 2
	s_add_u32 s98, s98, s84
	s_addc_u32 s99, s99, s85
	s_add_u32 s98, s98, 0x3c000
	s_addc_u32 s99, s99, 0
	global_load_dwordx4 v[134:137], v220, s[98:99] nt
	v_pk_mov_b32 v[82:83], v[80:81], v[78:79] op_sel:[1,0]
	v_mov_b32_e32 v81, v79
	v_pk_add_f32 v[78:79], v[82:83], v[80:81]
	s_waitcnt vmcnt(31)
	v_pk_mul_f32 v[80:81], v[6:7], v[138:139]
	v_add_f32_e32 v78, v78, v79
	s_nop 1
	v_add_f32_dpp v78, v78, v78 quad_perm:[1,0,3,2] row_mask:0xf bank_mask:0xf bound_ctrl:1
	s_nop 1
	v_add_f32_dpp v78, v78, v78 quad_perm:[2,3,0,1] row_mask:0xf bank_mask:0xf bound_ctrl:1
	s_nop 1
	v_add_f32_dpp v78, v78, v78 row_half_mirror row_mask:0xf bank_mask:0xf bound_ctrl:1
	s_nop 1
	v_add_f32_dpp v97, v78, v78 row_mirror row_mask:0xf bank_mask:0xf bound_ctrl:1
	v_pk_mul_f32 v[78:79], v[8:9], v[140:141]
	s_lshl_b64 s[98:99], s[4:5], 2
	s_add_u32 s98, s98, s84
	s_addc_u32 s99, s99, s85
	s_add_u32 s98, s98, 0x3e000
	s_addc_u32 s99, s99, 0
	global_load_dwordx4 v[138:141], v220, s[98:99] nt
	v_mul_f32_e32 v99, 0x3e38aa3b, v97
	v_pk_mov_b32 v[82:83], v[80:81], v[78:79] op_sel:[1,0]
	v_mov_b32_e32 v81, v79
	v_pk_add_f32 v[78:79], v[82:83], v[80:81]
	s_nop 0
	v_add_f32_e32 v78, v78, v79
	s_nop 1
	v_add_f32_dpp v78, v78, v78 quad_perm:[1,0,3,2] row_mask:0xf bank_mask:0xf bound_ctrl:1
	s_nop 1
	v_add_f32_dpp v78, v78, v78 quad_perm:[2,3,0,1] row_mask:0xf bank_mask:0xf bound_ctrl:1
	s_nop 1
	v_add_f32_dpp v78, v78, v78 row_half_mirror row_mask:0xf bank_mask:0xf bound_ctrl:1
	s_nop 1
	v_add_f32_dpp v79, v78, v78 row_mirror row_mask:0xf bank_mask:0xf bound_ctrl:1
	v_mul_f32_e32 v78, 0x3e38aa3b, v79
	v_max3_f32 v78, v85, v99, v78
	v_mov_b32_e32 v80, v78
	s_nop 1
	v_permlane16_swap_b32_e32 v78, v80
	v_max_f32_e32 v80, v80, v80
	v_max_f32_e32 v78, v78, v78
	v_max_f32_e32 v78, v78, v80
	v_mov_b32_e32 v80, v78
	s_nop 1
	v_permlane32_swap_b32_e32 v78, v80
	v_max3_f32 v156, v157, v78, v80
	v_fma_f32 v80, v154, s41, -v156
	v_sub_f32_e32 v78, v157, v156
	v_exp_f32_e32 v80, v80
	v_exp_f32_e32 v78, v78
	v_mov_b32_e32 v85, v80
	v_fmac_f32_e32 v85, v69, v78
	v_pk_mul_f32 v[82:83], v[144:145], v[80:81] op_sel_hi:[1,0]
	v_pk_mul_f32 v[80:81], v[142:143], v[80:81] op_sel_hi:[1,0]
	v_fma_f32 v69, v84, s41, -v156
	v_pk_fma_f32 v[74:75], v[74:75], v[78:79], v[80:81] op_sel_hi:[1,0,1]
	v_pk_fma_f32 v[72:73], v[72:73], v[78:79], v[82:83] op_sel_hi:[1,0,1]
	v_exp_f32_e32 v78, v69
	s_nop 0
	v_add_f32_e32 v69, v78, v85
	v_pk_fma_f32 v[72:73], v[148:149], v[78:79], v[72:73] op_sel_hi:[1,0,1]
	v_pk_fma_f32 v[74:75], v[146:147], v[78:79], v[74:75] op_sel_hi:[1,0,1]
	v_fma_f32 v78, v86, s41, -v156
	v_exp_f32_e32 v78, v78
	s_nop 0
	v_add_f32_e32 v69, v78, v69
	v_pk_fma_f32 v[74:75], v[150:151], v[78:79], v[74:75] op_sel_hi:[1,0,1]
	v_pk_fma_f32 v[72:73], v[152:153], v[78:79], v[72:73] op_sel_hi:[1,0,1]
	v_fma_f32 v78, v88, s41, -v156
	v_exp_f32_e32 v78, v78
	s_nop 0
	v_pk_fma_f32 v[64:65], v[64:65], v[78:79], v[72:73] op_sel_hi:[1,0,1]
	v_fma_f32 v72, v87, s41, -v156
	v_exp_f32_e32 v72, v72
	v_pk_fma_f32 v[62:63], v[62:63], v[78:79], v[74:75] op_sel_hi:[1,0,1]
	v_add_f32_e32 v69, v78, v69
	v_pk_fma_f32 v[58:59], v[58:59], v[72:73], v[62:63] op_sel_hi:[1,0,1]
	v_fma_f32 v62, v90, s41, -v156
	v_exp_f32_e32 v62, v62
	v_add_f32_e32 v69, v72, v69
	v_pk_fma_f32 v[60:61], v[60:61], v[72:73], v[64:65] op_sel_hi:[1,0,1]
	v_add_f32_e32 v63, v62, v69
	v_pk_fma_f32 v[54:55], v[54:55], v[62:63], v[58:59] op_sel_hi:[1,0,1]
	v_fma_f32 v58, v89, s41, -v156
	v_exp_f32_e32 v58, v58
	v_pk_fma_f32 v[56:57], v[56:57], v[62:63], v[60:61] op_sel_hi:[1,0,1]
	v_add_f32_e32 v59, v58, v63
	v_pk_fma_f32 v[50:51], v[50:51], v[58:59], v[54:55] op_sel_hi:[1,0,1]
	v_fma_f32 v54, v92, s41, -v156
	v_exp_f32_e32 v54, v54
	v_pk_fma_f32 v[52:53], v[52:53], v[58:59], v[56:57] op_sel_hi:[1,0,1]
	v_add_f32_e32 v55, v54, v59
	v_pk_fma_f32 v[46:47], v[46:47], v[54:55], v[50:51] op_sel_hi:[1,0,1]
	v_fma_f32 v50, v91, s41, -v156
	v_exp_f32_e32 v50, v50
	v_pk_fma_f32 v[48:49], v[48:49], v[54:55], v[52:53] op_sel_hi:[1,0,1]
	v_add_f32_e32 v51, v50, v55
	v_pk_fma_f32 v[42:43], v[42:43], v[50:51], v[46:47] op_sel_hi:[1,0,1]
	v_fma_f32 v46, v94, s41, -v156
	v_exp_f32_e32 v46, v46
	v_pk_fma_f32 v[44:45], v[44:45], v[50:51], v[48:49] op_sel_hi:[1,0,1]
	v_add_f32_e32 v47, v46, v51
	v_pk_fma_f32 v[38:39], v[38:39], v[46:47], v[42:43] op_sel_hi:[1,0,1]
	v_fma_f32 v42, v93, s41, -v156
	v_exp_f32_e32 v42, v42
	v_pk_fma_f32 v[40:41], v[40:41], v[46:47], v[44:45] op_sel_hi:[1,0,1]
	v_add_f32_e32 v43, v42, v47
	v_pk_fma_f32 v[34:35], v[34:35], v[42:43], v[38:39] op_sel_hi:[1,0,1]
	v_fma_f32 v38, v96, s41, -v156
	v_exp_f32_e32 v38, v38
	v_pk_fma_f32 v[36:37], v[36:37], v[42:43], v[40:41] op_sel_hi:[1,0,1]
	v_add_f32_e32 v39, v38, v43
	v_pk_fma_f32 v[30:31], v[30:31], v[38:39], v[34:35] op_sel_hi:[1,0,1]
	v_fma_f32 v34, v95, s41, -v156
	v_exp_f32_e32 v34, v34
	v_pk_fma_f32 v[32:33], v[32:33], v[38:39], v[36:37] op_sel_hi:[1,0,1]
	v_add_f32_e32 v35, v34, v39
	v_pk_fma_f32 v[26:27], v[26:27], v[34:35], v[30:31] op_sel_hi:[1,0,1]
	v_fma_f32 v30, v98, s41, -v156
	v_exp_f32_e32 v30, v30
	v_pk_fma_f32 v[28:29], v[28:29], v[34:35], v[32:33] op_sel_hi:[1,0,1]
	v_add_f32_e32 v31, v30, v35
	v_pk_fma_f32 v[22:23], v[22:23], v[30:31], v[26:27] op_sel_hi:[1,0,1]
	v_fma_f32 v26, v97, s41, -v156
	v_exp_f32_e32 v26, v26
	v_pk_fma_f32 v[24:25], v[24:25], v[30:31], v[28:29] op_sel_hi:[1,0,1]
	v_add_f32_e32 v27, v26, v31
	v_pk_fma_f32 v[18:19], v[18:19], v[26:27], v[22:23] op_sel_hi:[1,0,1]
	v_fma_f32 v22, v79, s41, -v156
	s_waitcnt vmcnt(31)
	v_mov_b64_e32 v[78:79], v[158:159]
	v_mov_b64_e32 v[80:81], v[160:161]
	s_waitcnt vmcnt(30)
	v_mov_b64_e32 v[82:83], v[162:163]
	v_mov_b64_e32 v[84:85], v[164:165]
	s_waitcnt vmcnt(29)
	v_mov_b64_e32 v[86:87], v[166:167]
	v_mov_b64_e32 v[88:89], v[168:169]
	s_waitcnt vmcnt(28)
	v_mov_b64_e32 v[90:91], v[170:171]
	v_mov_b64_e32 v[92:93], v[172:173]
	s_waitcnt vmcnt(27)
	v_mov_b64_e32 v[94:95], v[174:175]
	v_mov_b64_e32 v[96:97], v[176:177]
	s_waitcnt vmcnt(26)
	v_mov_b64_e32 v[98:99], v[178:179]
	v_mov_b64_e32 v[100:101], v[180:181]
	s_waitcnt vmcnt(25)
	v_mov_b64_e32 v[142:143], v[182:183]
	v_mov_b64_e32 v[144:145], v[184:185]
	s_waitcnt vmcnt(24)
	v_mov_b64_e32 v[146:147], v[186:187]
	v_mov_b64_e32 v[148:149], v[188:189]
	s_waitcnt vmcnt(23)
	v_mov_b64_e32 v[150:151], v[192:193]
	v_mov_b64_e32 v[152:153], v[194:195]
	s_waitcnt vmcnt(22)
	v_mov_b64_e32 v[62:63], v[196:197]
	v_mov_b64_e32 v[64:65], v[198:199]
	s_waitcnt vmcnt(21)
	v_mov_b64_e32 v[58:59], v[200:201]
	v_mov_b64_e32 v[60:61], v[202:203]
	s_waitcnt vmcnt(20)
	v_mov_b64_e32 v[54:55], v[204:205]
	v_mov_b64_e32 v[56:57], v[206:207]
	s_waitcnt vmcnt(19)
	v_mov_b64_e32 v[50:51], v[208:209]
	v_mov_b64_e32 v[52:53], v[210:211]
	s_waitcnt vmcnt(18)
	v_mov_b64_e32 v[46:47], v[212:213]
	v_mov_b64_e32 v[48:49], v[214:215]
	s_waitcnt vmcnt(17)
	v_mov_b64_e32 v[42:43], v[216:217]
	v_mov_b64_e32 v[44:45], v[218:219]
	s_waitcnt vmcnt(16)
	v_mov_b64_e32 v[38:39], v[224:225]
	v_mov_b64_e32 v[40:41], v[226:227]
	s_waitcnt vmcnt(15)
	v_mov_b64_e32 v[34:35], v[228:229]
	v_mov_b64_e32 v[36:37], v[230:231]
	s_waitcnt vmcnt(14)
	v_mov_b64_e32 v[30:31], v[232:233]
	v_mov_b64_e32 v[32:33], v[234:235]
	v_exp_f32_e32 v22, v22
	v_pk_fma_f32 v[20:21], v[20:21], v[26:27], v[24:25] op_sel_hi:[1,0,1]
	v_pk_fma_f32 v[74:75], v[14:15], v[22:23], v[18:19] op_sel_hi:[1,0,1]
	v_pk_fma_f32 v[72:73], v[16:17], v[22:23], v[20:21] op_sel_hi:[1,0,1]
	s_waitcnt vmcnt(11)
	v_mov_b64_e32 v[18:19], v[244:245]
	v_mov_b64_e32 v[20:21], v[246:247]
	s_waitcnt vmcnt(10)
	v_mov_b64_e32 v[14:15], v[252:253]
	v_mov_b64_e32 v[16:17], v[254:255]
	v_add_f32_e32 v69, v22, v27
	v_mov_b64_e32 v[26:27], v[236:237]
	v_mov_b64_e32 v[28:29], v[238:239]
	v_mov_b64_e32 v[22:23], v[240:241]
	v_mov_b64_e32 v[24:25], v[242:243]
	v_pk_mul_f32 v[80:81], v[8:9], v[80:81]
	v_pk_mul_f32 v[78:79], v[6:7], v[78:79]
	s_nop 0
	v_pk_mov_b32 v[154:155], v[78:79], v[80:81] op_sel:[1,0]
	v_mov_b32_e32 v79, v81
	v_pk_add_f32 v[78:79], v[154:155], v[78:79]
	s_nop 0
	v_add_f32_e32 v78, v78, v79
	s_nop 1
	v_add_f32_dpp v78, v78, v78 quad_perm:[1,0,3,2] row_mask:0xf bank_mask:0xf bound_ctrl:1
	s_nop 1
	v_add_f32_dpp v78, v78, v78 quad_perm:[2,3,0,1] row_mask:0xf bank_mask:0xf bound_ctrl:1
	s_nop 1
	v_add_f32_dpp v78, v78, v78 row_half_mirror row_mask:0xf bank_mask:0xf bound_ctrl:1
	v_pk_mul_f32 v[80:81], v[6:7], v[82:83]
	s_nop 0
	v_add_f32_dpp v154, v78, v78 row_mirror row_mask:0xf bank_mask:0xf bound_ctrl:1
	v_pk_mul_f32 v[78:79], v[8:9], v[84:85]
	s_nop 0
	v_pk_mov_b32 v[82:83], v[80:81], v[78:79] op_sel:[1,0]
	v_mov_b32_e32 v81, v79
	v_pk_add_f32 v[78:79], v[82:83], v[80:81]
	s_nop 0
	v_add_f32_e32 v78, v78, v79
	v_mul_f32_e32 v155, 0x3e38aa3b, v154
	s_nop 0
	v_add_f32_dpp v78, v78, v78 quad_perm:[1,0,3,2] row_mask:0xf bank_mask:0xf bound_ctrl:1
	v_pk_mul_f32 v[80:81], v[6:7], v[86:87]
	s_nop 0
	v_add_f32_dpp v78, v78, v78 quad_perm:[2,3,0,1] row_mask:0xf bank_mask:0xf bound_ctrl:1
	s_nop 1
	v_add_f32_dpp v78, v78, v78 row_half_mirror row_mask:0xf bank_mask:0xf bound_ctrl:1
	s_nop 1
	v_add_f32_dpp v157, v78, v78 row_mirror row_mask:0xf bank_mask:0xf bound_ctrl:1
	v_mul_f32_e32 v78, 0x3e38aa3b, v157
	v_max3_f32 v84, v155, s42, v78
	v_pk_mul_f32 v[78:79], v[8:9], v[88:89]
	s_nop 0
	v_pk_mov_b32 v[82:83], v[80:81], v[78:79] op_sel:[1,0]
	v_mov_b32_e32 v81, v79
	v_pk_add_f32 v[78:79], v[82:83], v[80:81]
	v_pk_mul_f32 v[80:81], v[6:7], v[90:91]
	v_add_f32_e32 v78, v78, v79
	s_nop 1
	v_add_f32_dpp v78, v78, v78 quad_perm:[1,0,3,2] row_mask:0xf bank_mask:0xf bound_ctrl:1
	s_nop 1
	v_add_f32_dpp v78, v78, v78 quad_perm:[2,3,0,1] row_mask:0xf bank_mask:0xf bound_ctrl:1
	s_nop 1
	v_add_f32_dpp v78, v78, v78 row_half_mirror row_mask:0xf bank_mask:0xf bound_ctrl:1
	s_nop 1
	v_add_f32_dpp v86, v78, v78 row_mirror row_mask:0xf bank_mask:0xf bound_ctrl:1
	v_pk_mul_f32 v[78:79], v[8:9], v[92:93]
	v_mul_f32_e32 v85, 0x3e38aa3b, v86
	v_pk_mov_b32 v[82:83], v[80:81], v[78:79] op_sel:[1,0]
	v_mov_b32_e32 v81, v79
	v_pk_add_f32 v[78:79], v[82:83], v[80:81]
	v_pk_mul_f32 v[80:81], v[6:7], v[94:95]
	v_add_f32_e32 v78, v78, v79
	s_nop 1
	v_add_f32_dpp v78, v78, v78 quad_perm:[1,0,3,2] row_mask:0xf bank_mask:0xf bound_ctrl:1
	s_nop 1
	v_add_f32_dpp v78, v78, v78 quad_perm:[2,3,0,1] row_mask:0xf bank_mask:0xf bound_ctrl:1
	s_nop 1
	v_add_f32_dpp v78, v78, v78 row_half_mirror row_mask:0xf bank_mask:0xf bound_ctrl:1
	s_nop 1
	v_add_f32_dpp v87, v78, v78 row_mirror row_mask:0xf bank_mask:0xf bound_ctrl:1
	v_mul_f32_e32 v78, 0x3e38aa3b, v87
	v_max3_f32 v84, v84, v85, v78
	v_pk_mul_f32 v[78:79], v[8:9], v[96:97]
	s_nop 0
	v_pk_mov_b32 v[82:83], v[80:81], v[78:79] op_sel:[1,0]
	v_mov_b32_e32 v81, v79
	v_pk_add_f32 v[78:79], v[82:83], v[80:81]
	v_pk_mul_f32 v[80:81], v[6:7], v[98:99]
	v_add_f32_e32 v78, v78, v79
	s_nop 1
	v_add_f32_dpp v78, v78, v78 quad_perm:[1,0,3,2] row_mask:0xf bank_mask:0xf bound_ctrl:1
	s_nop 1
	v_add_f32_dpp v78, v78, v78 quad_perm:[2,3,0,1] row_mask:0xf bank_mask:0xf bound_ctrl:1
	s_nop 1
	v_add_f32_dpp v78, v78, v78 row_half_mirror row_mask:0xf bank_mask:0xf bound_ctrl:1
	s_nop 1
	v_add_f32_dpp v88, v78, v78 row_mirror row_mask:0xf bank_mask:0xf bound_ctrl:1
	v_pk_mul_f32 v[78:79], v[8:9], v[100:101]
	v_mul_f32_e32 v85, 0x3e38aa3b, v88
	v_pk_mov_b32 v[82:83], v[80:81], v[78:79] op_sel:[1,0]
	v_mov_b32_e32 v81, v79
	v_pk_add_f32 v[78:79], v[82:83], v[80:81]
	s_waitcnt vmcnt(9)
	v_pk_mul_f32 v[80:81], v[6:7], v[102:103]
	v_add_f32_e32 v78, v78, v79
	s_nop 1
	v_add_f32_dpp v78, v78, v78 quad_perm:[1,0,3,2] row_mask:0xf bank_mask:0xf bound_ctrl:1
	s_nop 1
	v_add_f32_dpp v78, v78, v78 quad_perm:[2,3,0,1] row_mask:0xf bank_mask:0xf bound_ctrl:1
	s_nop 1
	v_add_f32_dpp v78, v78, v78 row_half_mirror row_mask:0xf bank_mask:0xf bound_ctrl:1
	s_nop 1
	v_add_f32_dpp v89, v78, v78 row_mirror row_mask:0xf bank_mask:0xf bound_ctrl:1
	v_mul_f32_e32 v78, 0x3e38aa3b, v89
	v_max3_f32 v84, v84, v85, v78
	v_pk_mul_f32 v[78:79], v[8:9], v[104:105]
	s_nop 0
	v_pk_mov_b32 v[82:83], v[80:81], v[78:79] op_sel:[1,0]
	v_mov_b32_e32 v81, v79
	v_pk_add_f32 v[78:79], v[82:83], v[80:81]
	s_waitcnt vmcnt(8)
	v_pk_mul_f32 v[80:81], v[6:7], v[106:107]
	v_add_f32_e32 v78, v78, v79
	s_nop 1
	v_add_f32_dpp v78, v78, v78 quad_perm:[1,0,3,2] row_mask:0xf bank_mask:0xf bound_ctrl:1
	s_nop 1
	v_add_f32_dpp v78, v78, v78 quad_perm:[2,3,0,1] row_mask:0xf bank_mask:0xf bound_ctrl:1
	s_nop 1
	v_add_f32_dpp v78, v78, v78 row_half_mirror row_mask:0xf bank_mask:0xf bound_ctrl:1
	s_nop 1
	v_add_f32_dpp v90, v78, v78 row_mirror row_mask:0xf bank_mask:0xf bound_ctrl:1
	v_pk_mul_f32 v[78:79], v[8:9], v[108:109]
	v_mul_f32_e32 v85, 0x3e38aa3b, v90
	v_pk_mov_b32 v[82:83], v[80:81], v[78:79] op_sel:[1,0]
	v_mov_b32_e32 v81, v79
	v_pk_add_f32 v[78:79], v[82:83], v[80:81]
	s_waitcnt vmcnt(7)
	v_pk_mul_f32 v[80:81], v[6:7], v[110:111]
	v_add_f32_e32 v78, v78, v79
	s_nop 1
	v_add_f32_dpp v78, v78, v78 quad_perm:[1,0,3,2] row_mask:0xf bank_mask:0xf bound_ctrl:1
	s_nop 1
	v_add_f32_dpp v78, v78, v78 quad_perm:[2,3,0,1] row_mask:0xf bank_mask:0xf bound_ctrl:1
	s_nop 1
	v_add_f32_dpp v78, v78, v78 row_half_mirror row_mask:0xf bank_mask:0xf bound_ctrl:1
	s_nop 1
	v_add_f32_dpp v91, v78, v78 row_mirror row_mask:0xf bank_mask:0xf bound_ctrl:1
	v_mul_f32_e32 v78, 0x3e38aa3b, v91
	v_max3_f32 v84, v84, v85, v78
	v_pk_mul_f32 v[78:79], v[8:9], v[112:113]
	s_nop 0
	v_pk_mov_b32 v[82:83], v[80:81], v[78:79] op_sel:[1,0]
	v_mov_b32_e32 v81, v79
	v_pk_add_f32 v[78:79], v[82:83], v[80:81]
	s_waitcnt vmcnt(6)
	v_pk_mul_f32 v[80:81], v[6:7], v[114:115]
	v_add_f32_e32 v78, v78, v79
	s_nop 1
	v_add_f32_dpp v78, v78, v78 quad_perm:[1,0,3,2] row_mask:0xf bank_mask:0xf bound_ctrl:1
	s_nop 1
	v_add_f32_dpp v78, v78, v78 quad_perm:[2,3,0,1] row_mask:0xf bank_mask:0xf bound_ctrl:1
	s_nop 1
	v_add_f32_dpp v78, v78, v78 row_half_mirror row_mask:0xf bank_mask:0xf bound_ctrl:1
	s_nop 1
	v_add_f32_dpp v92, v78, v78 row_mirror row_mask:0xf bank_mask:0xf bound_ctrl:1
	v_pk_mul_f32 v[78:79], v[8:9], v[116:117]
	v_mul_f32_e32 v85, 0x3e38aa3b, v92
	v_pk_mov_b32 v[82:83], v[80:81], v[78:79] op_sel:[1,0]
	v_mov_b32_e32 v81, v79
	v_pk_add_f32 v[78:79], v[82:83], v[80:81]
	s_waitcnt vmcnt(5)
	v_pk_mul_f32 v[80:81], v[6:7], v[118:119]
	v_add_f32_e32 v78, v78, v79
	s_nop 1
	v_add_f32_dpp v78, v78, v78 quad_perm:[1,0,3,2] row_mask:0xf bank_mask:0xf bound_ctrl:1
	s_nop 1
	v_add_f32_dpp v78, v78, v78 quad_perm:[2,3,0,1] row_mask:0xf bank_mask:0xf bound_ctrl:1
	s_nop 1
	v_add_f32_dpp v78, v78, v78 row_half_mirror row_mask:0xf bank_mask:0xf bound_ctrl:1
	s_nop 1
	v_add_f32_dpp v93, v78, v78 row_mirror row_mask:0xf bank_mask:0xf bound_ctrl:1
	v_mul_f32_e32 v78, 0x3e38aa3b, v93
	v_max3_f32 v84, v84, v85, v78
	v_pk_mul_f32 v[78:79], v[8:9], v[120:121]
	s_nop 0
	v_pk_mov_b32 v[82:83], v[80:81], v[78:79] op_sel:[1,0]
	v_mov_b32_e32 v81, v79
	v_pk_add_f32 v[78:79], v[82:83], v[80:81]
	s_waitcnt vmcnt(4)
	v_pk_mul_f32 v[80:81], v[6:7], v[122:123]
	v_add_f32_e32 v78, v78, v79
	v_cmp_ne_u32_e32 vcc, s0, v222
	s_nop 0
	v_add_f32_dpp v78, v78, v78 quad_perm:[1,0,3,2] row_mask:0xf bank_mask:0xf bound_ctrl:1
	v_cndmask_b32_e32 v76, v77, v76, vcc
	s_nop 0
	v_add_f32_dpp v78, v78, v78 quad_perm:[2,3,0,1] row_mask:0xf bank_mask:0xf bound_ctrl:1
	s_nop 1
	v_add_f32_dpp v78, v78, v78 row_half_mirror row_mask:0xf bank_mask:0xf bound_ctrl:1
	s_nop 1
	v_add_f32_dpp v94, v78, v78 row_mirror row_mask:0xf bank_mask:0xf bound_ctrl:1
	v_pk_mul_f32 v[78:79], v[8:9], v[124:125]
	v_mul_f32_e32 v85, 0x3e38aa3b, v94
	v_pk_mov_b32 v[82:83], v[80:81], v[78:79] op_sel:[1,0]
	v_mov_b32_e32 v81, v79
	v_pk_add_f32 v[78:79], v[82:83], v[80:81]
	s_waitcnt vmcnt(3)
	v_pk_mul_f32 v[80:81], v[6:7], v[126:127]
	v_add_f32_e32 v78, v78, v79
	s_nop 1
	v_add_f32_dpp v78, v78, v78 quad_perm:[1,0,3,2] row_mask:0xf bank_mask:0xf bound_ctrl:1
	s_nop 1
	v_add_f32_dpp v78, v78, v78 quad_perm:[2,3,0,1] row_mask:0xf bank_mask:0xf bound_ctrl:1
	s_nop 1
	v_add_f32_dpp v78, v78, v78 row_half_mirror row_mask:0xf bank_mask:0xf bound_ctrl:1
	s_nop 1
	v_add_f32_dpp v95, v78, v78 row_mirror row_mask:0xf bank_mask:0xf bound_ctrl:1
	v_mul_f32_e32 v78, 0x3e38aa3b, v95
	v_max3_f32 v84, v84, v85, v78
	v_pk_mul_f32 v[78:79], v[8:9], v[128:129]
	s_nop 0
	v_pk_mov_b32 v[82:83], v[80:81], v[78:79] op_sel:[1,0]
	v_mov_b32_e32 v81, v79
	v_pk_add_f32 v[78:79], v[82:83], v[80:81]
	s_waitcnt vmcnt(2)
	v_pk_mul_f32 v[80:81], v[6:7], v[130:131]
	v_add_f32_e32 v78, v78, v79
	s_nop 1
	v_add_f32_dpp v78, v78, v78 quad_perm:[1,0,3,2] row_mask:0xf bank_mask:0xf bound_ctrl:1
	s_nop 1
	v_add_f32_dpp v78, v78, v78 quad_perm:[2,3,0,1] row_mask:0xf bank_mask:0xf bound_ctrl:1
	s_nop 1
	v_add_f32_dpp v78, v78, v78 row_half_mirror row_mask:0xf bank_mask:0xf bound_ctrl:1
	s_nop 1
	v_add_f32_dpp v96, v78, v78 row_mirror row_mask:0xf bank_mask:0xf bound_ctrl:1
	v_pk_mul_f32 v[78:79], v[8:9], v[132:133]
	v_mul_f32_e32 v85, 0x3e38aa3b, v96
	v_pk_mov_b32 v[82:83], v[80:81], v[78:79] op_sel:[1,0]
	v_mov_b32_e32 v81, v79
	v_pk_add_f32 v[78:79], v[82:83], v[80:81]
	s_waitcnt vmcnt(1)
	v_pk_mul_f32 v[80:81], v[6:7], v[134:135]
	v_add_f32_e32 v78, v78, v79
	s_nop 1
	v_add_f32_dpp v78, v78, v78 quad_perm:[1,0,3,2] row_mask:0xf bank_mask:0xf bound_ctrl:1
	s_nop 1
	v_add_f32_dpp v78, v78, v78 quad_perm:[2,3,0,1] row_mask:0xf bank_mask:0xf bound_ctrl:1
	s_nop 1
	v_add_f32_dpp v78, v78, v78 row_half_mirror row_mask:0xf bank_mask:0xf bound_ctrl:1
	s_nop 1
	v_add_f32_dpp v97, v78, v78 row_mirror row_mask:0xf bank_mask:0xf bound_ctrl:1
	v_mul_f32_e32 v78, 0x3e38aa3b, v97
	v_max3_f32 v84, v84, v85, v78
	v_pk_mul_f32 v[78:79], v[8:9], v[136:137]
	s_nop 0
	v_pk_mov_b32 v[82:83], v[80:81], v[78:79] op_sel:[1,0]
	v_mov_b32_e32 v81, v79
	v_pk_add_f32 v[78:79], v[82:83], v[80:81]
	s_waitcnt vmcnt(0)
	v_pk_mul_f32 v[80:81], v[6:7], v[138:139]
	v_add_f32_e32 v78, v78, v79
	s_nop 1
	v_add_f32_dpp v78, v78, v78 quad_perm:[1,0,3,2] row_mask:0xf bank_mask:0xf bound_ctrl:1
	s_nop 1
	v_add_f32_dpp v78, v78, v78 quad_perm:[2,3,0,1] row_mask:0xf bank_mask:0xf bound_ctrl:1
	s_nop 1
	v_add_f32_dpp v78, v78, v78 row_half_mirror row_mask:0xf bank_mask:0xf bound_ctrl:1
	s_nop 1
	v_add_f32_dpp v98, v78, v78 row_mirror row_mask:0xf bank_mask:0xf bound_ctrl:1
	v_pk_mul_f32 v[78:79], v[8:9], v[140:141]
	v_mul_f32_e32 v85, 0x3e38aa3b, v98
	v_pk_mov_b32 v[82:83], v[80:81], v[78:79] op_sel:[1,0]
	v_mov_b32_e32 v81, v79
	v_pk_add_f32 v[78:79], v[82:83], v[80:81]
	s_nop 0
	v_add_f32_e32 v78, v78, v79
	s_nop 1
	v_add_f32_dpp v78, v78, v78 quad_perm:[1,0,3,2] row_mask:0xf bank_mask:0xf bound_ctrl:1
	s_nop 1
	v_add_f32_dpp v78, v78, v78 quad_perm:[2,3,0,1] row_mask:0xf bank_mask:0xf bound_ctrl:1
	s_nop 1
	v_add_f32_dpp v78, v78, v78 row_half_mirror row_mask:0xf bank_mask:0xf bound_ctrl:1
	s_nop 1
	v_add_f32_dpp v79, v78, v78 row_mirror row_mask:0xf bank_mask:0xf bound_ctrl:1
	v_mul_f32_e32 v78, 0x3e38aa3b, v79
	v_max3_f32 v78, v84, v85, v78
	v_mov_b32_e32 v80, v78
	s_nop 1
	v_permlane16_swap_b32_e32 v78, v80
	v_max_f32_e32 v80, v80, v80
	v_max_f32_e32 v78, v78, v78
	v_max_f32_e32 v78, v78, v80
	v_mov_b32_e32 v80, v78
	s_nop 1
	v_permlane32_swap_b32_e32 v78, v80
	v_max3_f32 v78, v156, v78, v80
	v_fma_f32 v81, v154, s41, -v78
	v_sub_f32_e32 v80, v156, v78
	v_exp_f32_e32 v82, v81
	v_exp_f32_e32 v80, v80
	v_mov_b32_e32 v81, v82
	v_fmac_f32_e32 v81, v69, v80
	v_pk_mul_f32 v[84:85], v[144:145], v[82:83] op_sel_hi:[1,0]
	v_pk_mul_f32 v[82:83], v[142:143], v[82:83] op_sel_hi:[1,0]
	v_fma_f32 v69, v157, s41, -v78
	v_pk_fma_f32 v[74:75], v[74:75], v[80:81], v[82:83] op_sel_hi:[1,0,1]
	v_pk_fma_f32 v[72:73], v[72:73], v[80:81], v[84:85] op_sel_hi:[1,0,1]
	v_exp_f32_e32 v80, v69
	s_nop 0
	v_add_f32_e32 v69, v80, v81
	v_pk_fma_f32 v[72:73], v[148:149], v[80:81], v[72:73] op_sel_hi:[1,0,1]
	v_pk_fma_f32 v[74:75], v[146:147], v[80:81], v[74:75] op_sel_hi:[1,0,1]
	v_fma_f32 v80, v86, s41, -v78
	v_exp_f32_e32 v80, v80
	s_nop 0
	v_add_f32_e32 v69, v80, v69
	v_pk_fma_f32 v[74:75], v[150:151], v[80:81], v[74:75] op_sel_hi:[1,0,1]
	v_pk_fma_f32 v[72:73], v[152:153], v[80:81], v[72:73] op_sel_hi:[1,0,1]
	v_fma_f32 v80, v87, s41, -v78
	v_exp_f32_e32 v80, v80
	s_nop 0
	v_pk_fma_f32 v[64:65], v[64:65], v[80:81], v[72:73] op_sel_hi:[1,0,1]
	v_fma_f32 v72, v88, s41, -v78
	v_exp_f32_e32 v72, v72
	v_pk_fma_f32 v[62:63], v[62:63], v[80:81], v[74:75] op_sel_hi:[1,0,1]
	v_add_f32_e32 v69, v80, v69
	v_pk_fma_f32 v[58:59], v[58:59], v[72:73], v[62:63] op_sel_hi:[1,0,1]
	v_fma_f32 v62, v89, s41, -v78
	v_exp_f32_e32 v62, v62
	v_add_f32_e32 v69, v72, v69
	v_pk_fma_f32 v[60:61], v[60:61], v[72:73], v[64:65] op_sel_hi:[1,0,1]
	v_add_f32_e32 v63, v62, v69
	v_pk_fma_f32 v[54:55], v[54:55], v[62:63], v[58:59] op_sel_hi:[1,0,1]
	v_fma_f32 v58, v90, s41, -v78
	v_exp_f32_e32 v58, v58
	v_pk_fma_f32 v[56:57], v[56:57], v[62:63], v[60:61] op_sel_hi:[1,0,1]
	v_add_f32_e32 v59, v58, v63
	v_pk_fma_f32 v[50:51], v[50:51], v[58:59], v[54:55] op_sel_hi:[1,0,1]
	v_fma_f32 v54, v91, s41, -v78
	v_exp_f32_e32 v54, v54
	v_pk_fma_f32 v[52:53], v[52:53], v[58:59], v[56:57] op_sel_hi:[1,0,1]
	v_add_f32_e32 v55, v54, v59
	v_pk_fma_f32 v[46:47], v[46:47], v[54:55], v[50:51] op_sel_hi:[1,0,1]
	v_fma_f32 v50, v92, s41, -v78
	v_exp_f32_e32 v50, v50
	v_pk_fma_f32 v[48:49], v[48:49], v[54:55], v[52:53] op_sel_hi:[1,0,1]
	v_add_f32_e32 v51, v50, v55
	v_pk_fma_f32 v[42:43], v[42:43], v[50:51], v[46:47] op_sel_hi:[1,0,1]
	v_fma_f32 v46, v93, s41, -v78
	v_exp_f32_e32 v46, v46
	v_pk_fma_f32 v[44:45], v[44:45], v[50:51], v[48:49] op_sel_hi:[1,0,1]
	v_add_f32_e32 v47, v46, v51
	v_pk_fma_f32 v[38:39], v[38:39], v[46:47], v[42:43] op_sel_hi:[1,0,1]
	v_fma_f32 v42, v94, s41, -v78
	v_exp_f32_e32 v42, v42
	v_pk_fma_f32 v[40:41], v[40:41], v[46:47], v[44:45] op_sel_hi:[1,0,1]
	v_add_f32_e32 v43, v42, v47
	v_pk_fma_f32 v[34:35], v[34:35], v[42:43], v[38:39] op_sel_hi:[1,0,1]
	v_fma_f32 v38, v95, s41, -v78
	v_exp_f32_e32 v38, v38
	v_pk_fma_f32 v[36:37], v[36:37], v[42:43], v[40:41] op_sel_hi:[1,0,1]
	v_add_f32_e32 v39, v38, v43
	v_pk_fma_f32 v[30:31], v[30:31], v[38:39], v[34:35] op_sel_hi:[1,0,1]
	v_fma_f32 v34, v96, s41, -v78
	v_exp_f32_e32 v34, v34
	v_pk_fma_f32 v[32:33], v[32:33], v[38:39], v[36:37] op_sel_hi:[1,0,1]
	v_add_f32_e32 v35, v34, v39
	v_pk_fma_f32 v[26:27], v[26:27], v[34:35], v[30:31] op_sel_hi:[1,0,1]
	v_fma_f32 v30, v97, s41, -v78
	v_exp_f32_e32 v30, v30
	v_pk_fma_f32 v[28:29], v[28:29], v[34:35], v[32:33] op_sel_hi:[1,0,1]
	v_add_f32_e32 v31, v30, v35
	v_pk_fma_f32 v[22:23], v[22:23], v[30:31], v[26:27] op_sel_hi:[1,0,1]
	v_fma_f32 v26, v98, s41, -v78
	v_exp_f32_e32 v26, v26
	v_pk_fma_f32 v[24:25], v[24:25], v[30:31], v[28:29] op_sel_hi:[1,0,1]
	v_add_f32_e32 v27, v26, v31
	v_pk_fma_f32 v[18:19], v[18:19], v[26:27], v[22:23] op_sel_hi:[1,0,1]
	v_fma_f32 v22, v79, s41, -v78
	v_exp_f32_e32 v22, v22
	v_pk_fma_f32 v[20:21], v[20:21], v[26:27], v[24:25] op_sel_hi:[1,0,1]
	v_add_f32_e32 v69, v22, v27
	v_pk_fma_f32 v[74:75], v[16:17], v[22:23], v[20:21] op_sel_hi:[1,0,1]
	v_pk_fma_f32 v[72:73], v[14:15], v[22:23], v[18:19] op_sel_hi:[1,0,1]
	s_cmp_eq_u32 s13, 0
	s_cbranch_scc0 .LBB0_347
	v_pk_mul_f32 v[8:9], v[8:9], v[12:13]
	v_pk_mul_f32 v[6:7], v[6:7], v[10:11]
	v_cmp_ge_u32_e32 vcc, s12, v67
	v_pk_mov_b32 v[10:11], v[6:7], v[8:9] op_sel:[1,0]
	v_mov_b32_e32 v7, v9
	v_pk_add_f32 v[6:7], v[10:11], v[6:7]
	s_nop 0
	v_add_f32_e32 v6, v6, v7
	v_mov_b32_e32 v7, 0xff800000
	s_nop 0
	v_add_f32_dpp v6, v6, v6 quad_perm:[1,0,3,2] row_mask:0xf bank_mask:0xf bound_ctrl:1
	s_nop 1
	v_add_f32_dpp v6, v6, v6 quad_perm:[2,3,0,1] row_mask:0xf bank_mask:0xf bound_ctrl:1
	s_nop 1
	v_add_f32_dpp v6, v6, v6 row_half_mirror row_mask:0xf bank_mask:0xf bound_ctrl:1
	s_nop 1
	v_add_f32_dpp v6, v6, v6 row_mirror row_mask:0xf bank_mask:0xf bound_ctrl:1
	v_mul_f32_e32 v6, 0x3e38aa3b, v6
	v_cndmask_b32_e32 v6, v7, v6, vcc
	v_mov_b32_e32 v7, v6
	v_mov_b32_e32 v8, v6
	s_nop 1
	v_permlane16_swap_b32_e32 v7, v8
	v_max_f32_e32 v8, v8, v8
	v_max_f32_e32 v7, v7, v7
	v_max_f32_e32 v7, v7, v8
	v_mov_b32_e32 v8, v7
	s_nop 1
	v_permlane32_swap_b32_e32 v7, v8
	v_max3_f32 v7, v78, v7, v8
	v_sub_f32_e32 v6, v6, v7
	v_exp_f32_e32 v10, v6
	v_sub_f32_e32 v6, v78, v7
	v_exp_f32_e32 v12, v6
	v_cmp_gt_u32_e32 vcc, 16, v190
	v_pk_mul_f32 v[2:3], v[2:3], v[10:11] op_sel_hi:[1,0]
	v_pk_mul_f32 v[4:5], v[4:5], v[10:11] op_sel_hi:[1,0]
	v_pk_fma_f32 v[2:3], v[72:73], v[12:13], v[2:3] op_sel_hi:[1,0,1]
	v_pk_fma_f32 v[14:15], v[74:75], v[12:13], v[4:5] op_sel_hi:[1,0,1]
	v_mov_b32_e32 v5, v3
	s_nop 1
	v_permlane16_swap_b32_e32 v3, v5
	v_fmac_f32_e32 v10, v69, v12
	v_mov_b32_e32 v4, v2
	v_add_f32_e32 v6, v3, v5
	v_mov_b32_e32 v3, v14
	v_mov_b32_e32 v7, v15
	v_mov_b32_e32 v11, v10
	v_permlane16_swap_b32_e32 v2, v4
	v_permlane16_swap_b32_e32 v14, v3
	v_permlane16_swap_b32_e32 v15, v7
	v_permlane16_swap_b32_e32 v10, v11
	v_add_f32_e32 v2, v2, v4
	v_add_f32_e32 v3, v14, v3
	v_add_f32_e32 v7, v15, v7
	v_add_f32_e32 v10, v10, v11
	v_mov_b32_e32 v4, v2
	v_mov_b32_e32 v8, v6
	v_mov_b32_e32 v5, v3
	v_mov_b32_e32 v9, v7
	v_mov_b32_e32 v11, v10
	v_permlane32_swap_b32_e32 v2, v4
	v_permlane32_swap_b32_e32 v6, v8
	v_permlane32_swap_b32_e32 v3, v5
	v_permlane32_swap_b32_e32 v7, v9
	v_permlane32_swap_b32_e32 v10, v11
	s_and_saveexec_b64 s[4:5], vcc
	v_readlane_b32 s20, v250, 10
	v_readlane_b32 s21, v250, 11
	s_cbranch_execz .LBB0_350
	v_add_f32_e32 v10, v10, v11
	v_div_scale_f32 v11, s[0:1], v10, v10, 1.0
	v_rcp_f32_e32 v12, v11
	v_div_scale_f32 v13, vcc, 1.0, v10, 1.0
	v_pk_add_f32 v[6:7], v[6:7], v[8:9]
	v_fma_f32 v14, -v11, v12, 1.0
	v_fmac_f32_e32 v12, v14, v12
	v_mul_f32_e32 v14, v13, v12
	v_fma_f32 v15, -v11, v14, v13
	v_fmac_f32_e32 v14, v15, v12
	v_fma_f32 v11, -v11, v14, v13
	v_div_fmas_f32 v11, v11, v12, v14
	v_div_fixup_f32 v10, v11, v10, 1.0
	v_pk_add_f32 v[2:3], v[2:3], v[4:5]
	v_pk_mul_f32 v[4:5], v[6:7], v[10:11] op_sel_hi:[1,0]
	v_pk_mul_f32 v[2:3], v[2:3], v[10:11] op_sel_hi:[1,0]
	v_mov_b32_e32 v6, 1
	v_and_b32_sdwa v7, v3, v6 dst_sel:DWORD dst_unused:UNUSED_PAD src0_sel:WORD_1 src1_sel:DWORD
	s_movk_i32 s0, 0x7fff
	v_and_b32_sdwa v8, v2, v6 dst_sel:DWORD dst_unused:UNUSED_PAD src0_sel:WORD_1 src1_sel:DWORD
	v_add3_u32 v3, v3, v7, s0
	v_and_b32_sdwa v7, v5, v6 dst_sel:DWORD dst_unused:UNUSED_PAD src0_sel:WORD_1 src1_sel:DWORD
	v_and_b32_sdwa v6, v4, v6 dst_sel:DWORD dst_unused:UNUSED_PAD src0_sel:WORD_1 src1_sel:DWORD
	v_add3_u32 v2, v2, v8, s0
	v_add3_u32 v5, v5, v7, s0
	v_add3_u32 v4, v4, v6, s0
	v_readlane_b32 s0, v250, 12
	v_readlane_b32 s1, v250, 13
	s_add_u32 s0, s0, s2
	s_addc_u32 s1, s1, s3
	s_lshl_b32 s2, s11, 1
	v_and_b32_e32 v5, 0xffff0000, v5
	v_and_b32_e32 v4, 0xffff0000, v4
	s_add_u32 s0, s0, s2
	v_or_b32_sdwa v3, v5, v3 dst_sel:DWORD dst_unused:UNUSED_PAD src0_sel:DWORD src1_sel:WORD_1
	v_or_b32_sdwa v2, v4, v2 dst_sel:DWORD dst_unused:UNUSED_PAD src0_sel:DWORD src1_sel:WORD_1
	s_addc_u32 s1, s1, 0
	v_lshlrev_b32_e32 v4, 1, v66
	global_store_dwordx2 v4, v[2:3], s[0:1] offset:1024
